# odd-layer pool + SGU-prep: the 62 serialized global loads per thread (each followed by vmcnt(0)) issued in three batches up front, consumers read register copies
# speedup vs baseline: 1.0118x; 1.0118x over previous
; __device__ __forceinline__ void UNPACK8(const u32x4 q, float (&f)[8]) { f[0] = bflo(q.x); f[1] = bfhi(q.x); f[2] = bflo(q.y); f[3] = bfhi(q.y); f[4] = bflo(q.z); f[5] = bfhi(q.z); f[6] = bflo(q.w); f[7] = bfhi(q.w); }
; __device__ __forceinline__ void pool_chunk(PCP p, int chunk, int tid) {
;     const bf16_t* proj = (const bf16_t*)(p->ws + WS_PROJ); bf16_t* pooled = (bf16_t*)(p->ws + WS_A2);
;     { const int idx = chunk * 512 + tid;
;         const int t0 = (idx >> 6) * 16, c = (idx & 63) * 8, pos0 = t0 & (SEQ - 1), w = 2 << (c >> 7);
;         float s[8];
; #pragma unroll
;         for (int e = 0; e < 8; ++e) s[e] = 0.f;
; #pragma unroll
;         for (int k = 1; k < 16; ++k) { if (k < w && k <= pos0) { const u32x4 zw = *(const u32x4*)(proj + (size_t)(t0 - k) * 1536 + c); float q[8]; UNPACK8(zw, q);
; #pragma unroll
;             for (int e = 0; e < 8; ++e) s[e] += q[e]; } }
.LBB0_326:
	v_lshl_add_u32 v0, s2, 9, v66
	v_ashrrev_i32_e32 v76, 2, v0
	v_and_b32_e32 v77, 0xff0, v76
	v_mov_b32_e32 v54, 0
	v_and_b32_e32 v4, -16, v76
	v_add_u32_e32 v84, -1, v4
	v_mad_i64_i32 v[86:87], vcc, v84, s45, v[8:9]
	global_load_dwordx4 v[84:87], v[86:87], off
	v_add_u32_e32 v88, -2, v4
	v_mad_i64_i32 v[90:91], vcc, v88, s45, v[8:9]
	global_load_dwordx4 v[88:91], v[90:91], off
	v_add_u32_e32 v92, -3, v4
	v_mad_i64_i32 v[94:95], vcc, v92, s45, v[8:9]
	global_load_dwordx4 v[92:95], v[94:95], off
	v_add_u32_e32 v96, -4, v4
	v_mad_i64_i32 v[98:99], vcc, v96, s45, v[8:9]
	global_load_dwordx4 v[96:99], v[98:99], off
	v_add_u32_e32 v100, -5, v4
	v_mad_i64_i32 v[102:103], vcc, v100, s45, v[8:9]
	global_load_dwordx4 v[100:103], v[102:103], off
	v_add_u32_e32 v104, -6, v4
	v_mad_i64_i32 v[106:107], vcc, v104, s45, v[8:9]
	global_load_dwordx4 v[104:107], v[106:107], off
	v_add_u32_e32 v108, -7, v4
	v_mad_i64_i32 v[110:111], vcc, v108, s45, v[8:9]
	global_load_dwordx4 v[108:111], v[110:111], off
	v_add_u32_e32 v112, -8, v4
	v_mad_i64_i32 v[114:115], vcc, v112, s45, v[8:9]
	global_load_dwordx4 v[112:115], v[114:115], off
	v_add_u32_e32 v116, -9, v4
	v_mad_i64_i32 v[118:119], vcc, v116, s45, v[8:9]
	global_load_dwordx4 v[116:119], v[118:119], off
	v_add_u32_e32 v120, -10, v4
	v_mad_i64_i32 v[122:123], vcc, v120, s45, v[8:9]
	global_load_dwordx4 v[120:123], v[122:123], off
	v_add_u32_e32 v124, -11, v4
	v_mad_i64_i32 v[126:127], vcc, v124, s45, v[8:9]
	global_load_dwordx4 v[124:127], v[126:127], off
	v_add_u32_e32 v128, -12, v4
	v_mad_i64_i32 v[130:131], vcc, v128, s45, v[8:9]
	global_load_dwordx4 v[128:131], v[130:131], off
	v_add_u32_e32 v132, -13, v4
	v_mad_i64_i32 v[134:135], vcc, v132, s45, v[8:9]
	global_load_dwordx4 v[132:135], v[134:135], off
	v_add_u32_e32 v136, -14, v4
	v_mad_i64_i32 v[138:139], vcc, v136, s45, v[8:9]
	global_load_dwordx4 v[136:139], v[138:139], off
	v_add_u32_e32 v140, -15, v4
	v_mad_i64_i32 v[142:143], vcc, v140, s45, v[8:9]
	global_load_dwordx4 v[140:143], v[142:143], off
	v_or_b32_e32 v144, 0, v4
	v_mad_i64_i32 v[146:147], vcc, v144, s45, v[8:9]
	global_load_dwordx4 v[144:147], v[146:147], off
	v_or_b32_e32 v148, 1, v4
	v_mad_i64_i32 v[150:151], vcc, v148, s45, v[8:9]
	global_load_dwordx4 v[148:151], v[150:151], off
	v_or_b32_e32 v152, 2, v4
	v_mad_i64_i32 v[154:155], vcc, v152, s45, v[8:9]
	global_load_dwordx4 v[152:155], v[154:155], off
	v_or_b32_e32 v156, 3, v4
	v_mad_i64_i32 v[158:159], vcc, v156, s45, v[8:9]
	global_load_dwordx4 v[156:159], v[158:159], off
	v_or_b32_e32 v166, 4, v4
	v_mad_i64_i32 v[168:169], vcc, v166, s45, v[8:9]
	global_load_dwordx4 v[166:169], v[168:169], off
	v_or_b32_e32 v178, 5, v4
	v_mad_i64_i32 v[180:181], vcc, v178, s45, v[8:9]
	global_load_dwordx4 v[178:181], v[180:181], off
	v_or_b32_e32 v182, 6, v4
	v_mad_i64_i32 v[184:185], vcc, v182, s45, v[8:9]
	global_load_dwordx4 v[182:185], v[184:185], off
	v_or_b32_e32 v186, 7, v4
	v_mad_i64_i32 v[188:189], vcc, v186, s45, v[8:9]
	global_load_dwordx4 v[186:189], v[188:189], off
	v_or_b32_e32 v190, 8, v4
	v_mad_i64_i32 v[192:193], vcc, v190, s45, v[8:9]
	global_load_dwordx4 v[190:193], v[192:193], off
	v_or_b32_e32 v194, 9, v4
	v_mad_i64_i32 v[196:197], vcc, v194, s45, v[8:9]
	global_load_dwordx4 v[194:197], v[196:197], off
	v_or_b32_e32 v198, 10, v4
	v_mad_i64_i32 v[200:201], vcc, v198, s45, v[8:9]
	global_load_dwordx4 v[198:201], v[200:201], off
	v_or_b32_e32 v202, 11, v4
	v_mad_i64_i32 v[204:205], vcc, v202, s45, v[8:9]
	global_load_dwordx4 v[202:205], v[204:205], off
	v_or_b32_e32 v216, 12, v4
	v_mad_i64_i32 v[218:219], vcc, v216, s45, v[8:9]
	global_load_dwordx4 v[216:219], v[218:219], off
	v_or_b32_e32 v220, 13, v4
	v_mad_i64_i32 v[222:223], vcc, v220, s45, v[8:9]
	global_load_dwordx4 v[220:223], v[222:223], off
	v_or_b32_e32 v226, 14, v4
	v_mad_i64_i32 v[228:229], vcc, v226, s45, v[8:9]
	global_load_dwordx4 v[226:229], v[228:229], off
	v_or_b32_e32 v230, 15, v4
	v_mad_i64_i32 v[232:233], vcc, v230, s45, v[8:9]
	global_load_dwordx4 v[230:233], v[232:233], off
	s_waitcnt vmcnt(0)
	v_cmp_eq_u32_e32 vcc, 0, v77
	v_cmp_ne_u32_e64 s[16:17], 0, v77
	v_mov_b32_e32 v55, 0
	v_mov_b32_e32 v0, 0
	v_mov_b32_e32 v1, 0
	v_mov_b32_e32 v2, 0
	v_mov_b32_e32 v3, v54
	v_mov_b32_e32 v6, v54
	v_mov_b32_e32 v7, v54
	v_mov_b32_e32 v52, 0
	v_mov_b32_e32 v53, 0
	s_and_saveexec_b64 s[4:5], s[16:17]
	s_cbranch_execz .LBB0_407
	v_add_u32_e32 v0, -1, v4
	v_mad_i64_i32 v[0:1], s[16:17], v0, s45, v[8:9]
	v_mov_b32_e32 v0, v84
	v_mov_b32_e32 v1, v85
	v_mov_b32_e32 v2, v86
	v_mov_b32_e32 v3, v87
	v_lshlrev_b32_e32 v6, 16, v0
	v_and_b32_e32 v7, 0xffff0000, v0
	v_lshlrev_b32_e32 v54, 16, v2
	v_and_b32_e32 v55, 0xffff0000, v2
	v_lshlrev_b32_e32 v56, 16, v3
	v_and_b32_e32 v57, 0xffff0000, v3
	v_lshlrev_b32_e32 v52, 16, v1
	v_and_b32_e32 v53, 0xffff0000, v1
	v_pk_add_f32 v[0:1], v[6:7], 0 op_sel_hi:[1,0]
	v_pk_add_f32 v[6:7], v[54:55], 0 op_sel_hi:[1,0]
	v_pk_add_f32 v[54:55], v[56:57], 0 op_sel_hi:[1,0]
	v_pk_add_f32 v[2:3], v[52:53], 0 op_sel_hi:[1,0]
	v_mov_b32_e32 v52, v54
	v_mov_b32_e32 v53, v55
	s_or_b64 exec, exec, s[4:5]
	s_nor_b64 s[4:5], s[8:9], vcc
	s_and_saveexec_b64 s[16:17], s[4:5]
	s_cbranch_execnz .LBB0_408

; __device__ __forceinline__ void UNPACK8(const u32x4 q, float (&f)[8]) { f[0] = bflo(q.x); f[1] = bfhi(q.x); f[2] = bflo(q.y); f[3] = bfhi(q.y); f[4] = bflo(q.z); f[5] = bfhi(q.z); f[6] = bflo(q.w); f[7] = bfhi(q.w); }
; __device__ __forceinline__ void pool_chunk(PCP p, int chunk, int tid) {
;     ...
;         for (int k = 1; k < 16; ++k) { if (k < w && k <= pos0) { const u32x4 zw = *(const u32x4*)(proj + (size_t)(t0 - k) * 1536 + c); float q[8]; UNPACK8(zw, q);
; #pragma unroll
;             for (int e = 0; e < 8; ++e) s[e] += q[e]; } }
.LBB0_329:
	v_add_u32_e32 v5, -3, v4
	v_mad_i64_i32 v[54:55], s[4:5], v5, s45, v[8:9]
	v_mov_b32_e32 v54, v92
	v_mov_b32_e32 v55, v93
	v_mov_b32_e32 v56, v94
	v_mov_b32_e32 v57, v95
	v_lshlrev_b32_e32 v58, 16, v54
	v_and_b32_e32 v59, 0xffff0000, v54
	v_lshlrev_b32_e32 v54, 16, v55
	v_and_b32_e32 v55, 0xffff0000, v55
	v_pk_add_f32 v[2:3], v[2:3], v[54:55]
	v_lshlrev_b32_e32 v54, 16, v56
	v_and_b32_e32 v55, 0xffff0000, v56
	v_pk_add_f32 v[6:7], v[6:7], v[54:55]
	v_lshlrev_b32_e32 v54, 16, v57
	v_and_b32_e32 v55, 0xffff0000, v57
	v_pk_add_f32 v[0:1], v[0:1], v[58:59]
	v_pk_add_f32 v[52:53], v[52:53], v[54:55]
	s_or_b64 exec, exec, s[16:17]
	s_nor_b64 s[4:5], s[10:11], vcc
	s_and_saveexec_b64 s[16:17], s[4:5]
	s_cbranch_execnz .LBB0_410

; __device__ __forceinline__ void UNPACK8(const u32x4 q, float (&f)[8]) { f[0] = bflo(q.x); f[1] = bfhi(q.x); f[2] = bflo(q.y); f[3] = bfhi(q.y); f[4] = bflo(q.z); f[5] = bfhi(q.z); f[6] = bflo(q.w); f[7] = bfhi(q.w); }
; __device__ __forceinline__ void pool_chunk(PCP p, int chunk, int tid) {
;     ...
;         for (int k = 1; k < 16; ++k) { if (k < w && k <= pos0) { const u32x4 zw = *(const u32x4*)(proj + (size_t)(t0 - k) * 1536 + c); float q[8]; UNPACK8(zw, q);
; #pragma unroll
;             for (int e = 0; e < 8; ++e) s[e] += q[e]; } }
.LBB0_331:
	v_add_u32_e32 v5, -5, v4
	v_mad_i64_i32 v[54:55], s[28:29], v5, s45, v[8:9]
	v_mov_b32_e32 v54, v100
	v_mov_b32_e32 v55, v101
	v_mov_b32_e32 v56, v102
	v_mov_b32_e32 v57, v103
	v_lshlrev_b32_e32 v58, 16, v54
	v_and_b32_e32 v59, 0xffff0000, v54
	v_lshlrev_b32_e32 v54, 16, v55
	v_and_b32_e32 v55, 0xffff0000, v55
	v_pk_add_f32 v[2:3], v[2:3], v[54:55]
	v_lshlrev_b32_e32 v54, 16, v56
	v_and_b32_e32 v55, 0xffff0000, v56
	v_pk_add_f32 v[6:7], v[6:7], v[54:55]
	v_lshlrev_b32_e32 v54, 16, v57
	v_and_b32_e32 v55, 0xffff0000, v57
	v_pk_add_f32 v[0:1], v[0:1], v[58:59]
	v_pk_add_f32 v[52:53], v[52:53], v[54:55]
	s_or_b64 exec, exec, s[16:17]
	s_and_saveexec_b64 s[16:17], s[4:5]
	s_cbranch_execnz .LBB0_412

; __device__ __forceinline__ void UNPACK8(const u32x4 q, float (&f)[8]) { f[0] = bflo(q.x); f[1] = bfhi(q.x); f[2] = bflo(q.y); f[3] = bfhi(q.y); f[4] = bflo(q.z); f[5] = bfhi(q.z); f[6] = bflo(q.w); f[7] = bfhi(q.w); }
; __device__ __forceinline__ void pool_chunk(PCP p, int chunk, int tid) {
;     ...
;         for (int k = 1; k < 16; ++k) { if (k < w && k <= pos0) { const u32x4 zw = *(const u32x4*)(proj + (size_t)(t0 - k) * 1536 + c); float q[8]; UNPACK8(zw, q);
; #pragma unroll
;             for (int e = 0; e < 8; ++e) s[e] += q[e]; } }
.LBB0_333:
	v_add_u32_e32 v5, -7, v4
	v_mad_i64_i32 v[54:55], s[4:5], v5, s45, v[8:9]
	v_mov_b32_e32 v54, v108
	v_mov_b32_e32 v55, v109
	v_mov_b32_e32 v56, v110
	v_mov_b32_e32 v57, v111
	v_lshlrev_b32_e32 v58, 16, v54
	v_and_b32_e32 v59, 0xffff0000, v54
	v_lshlrev_b32_e32 v54, 16, v55
	v_and_b32_e32 v55, 0xffff0000, v55
	v_pk_add_f32 v[2:3], v[2:3], v[54:55]
	v_lshlrev_b32_e32 v54, 16, v56
	v_and_b32_e32 v55, 0xffff0000, v56
	v_pk_add_f32 v[6:7], v[6:7], v[54:55]
	v_lshlrev_b32_e32 v54, 16, v57
	v_and_b32_e32 v55, 0xffff0000, v57
	v_pk_add_f32 v[0:1], v[0:1], v[58:59]
	v_pk_add_f32 v[52:53], v[52:53], v[54:55]
	s_or_b64 exec, exec, s[16:17]
	s_nor_b64 s[4:5], s[12:13], vcc
	s_and_saveexec_b64 s[16:17], s[4:5]
	s_cbranch_execnz .LBB0_414

; __device__ __forceinline__ void UNPACK8(const u32x4 q, float (&f)[8]) { f[0] = bflo(q.x); f[1] = bfhi(q.x); f[2] = bflo(q.y); f[3] = bfhi(q.y); f[4] = bflo(q.z); f[5] = bfhi(q.z); f[6] = bflo(q.w); f[7] = bfhi(q.w); }
; __device__ __forceinline__ void pool_chunk(PCP p, int chunk, int tid) {
;     ...
;         for (int k = 1; k < 16; ++k) { if (k < w && k <= pos0) { const u32x4 zw = *(const u32x4*)(proj + (size_t)(t0 - k) * 1536 + c); float q[8]; UNPACK8(zw, q);
; #pragma unroll
;             for (int e = 0; e < 8; ++e) s[e] += q[e]; } }
.LBB0_335:
	v_add_u32_e32 v5, -9, v4
	v_mad_i64_i32 v[54:55], s[28:29], v5, s45, v[8:9]
	v_mov_b32_e32 v54, v116
	v_mov_b32_e32 v55, v117
	v_mov_b32_e32 v56, v118
	v_mov_b32_e32 v57, v119
	v_lshlrev_b32_e32 v58, 16, v54
	v_and_b32_e32 v59, 0xffff0000, v54
	v_lshlrev_b32_e32 v54, 16, v55
	v_and_b32_e32 v55, 0xffff0000, v55
	v_pk_add_f32 v[2:3], v[2:3], v[54:55]
	v_lshlrev_b32_e32 v54, 16, v56
	v_and_b32_e32 v55, 0xffff0000, v56
	v_pk_add_f32 v[6:7], v[6:7], v[54:55]
	v_lshlrev_b32_e32 v54, 16, v57
	v_and_b32_e32 v55, 0xffff0000, v57
	v_pk_add_f32 v[0:1], v[0:1], v[58:59]
	v_pk_add_f32 v[52:53], v[52:53], v[54:55]
	s_or_b64 exec, exec, s[16:17]
	s_and_saveexec_b64 s[16:17], s[4:5]
	s_cbranch_execnz .LBB0_416

; __device__ __forceinline__ void UNPACK8(const u32x4 q, float (&f)[8]) { f[0] = bflo(q.x); f[1] = bfhi(q.x); f[2] = bflo(q.y); f[3] = bfhi(q.y); f[4] = bflo(q.z); f[5] = bfhi(q.z); f[6] = bflo(q.w); f[7] = bfhi(q.w); }
; __device__ __forceinline__ void pool_chunk(PCP p, int chunk, int tid) {
;     ...
;         for (int k = 1; k < 16; ++k) { if (k < w && k <= pos0) { const u32x4 zw = *(const u32x4*)(proj + (size_t)(t0 - k) * 1536 + c); float q[8]; UNPACK8(zw, q);
; #pragma unroll
;             for (int e = 0; e < 8; ++e) s[e] += q[e]; } }
.LBB0_337:
	v_add_u32_e32 v5, -11, v4
	v_mad_i64_i32 v[54:55], s[28:29], v5, s45, v[8:9]
	v_mov_b32_e32 v54, v124
	v_mov_b32_e32 v55, v125
	v_mov_b32_e32 v56, v126
	v_mov_b32_e32 v57, v127
	v_lshlrev_b32_e32 v58, 16, v54
	v_and_b32_e32 v59, 0xffff0000, v54
	v_lshlrev_b32_e32 v54, 16, v55
	v_and_b32_e32 v55, 0xffff0000, v55
	v_pk_add_f32 v[2:3], v[2:3], v[54:55]
	v_lshlrev_b32_e32 v54, 16, v56
	v_and_b32_e32 v55, 0xffff0000, v56
	v_pk_add_f32 v[6:7], v[6:7], v[54:55]
	v_lshlrev_b32_e32 v54, 16, v57
	v_and_b32_e32 v55, 0xffff0000, v57
	v_pk_add_f32 v[0:1], v[0:1], v[58:59]
	v_pk_add_f32 v[52:53], v[52:53], v[54:55]
	s_or_b64 exec, exec, s[16:17]
	s_and_saveexec_b64 s[16:17], s[4:5]
	s_cbranch_execnz .LBB0_418

; __device__ __forceinline__ void UNPACK8(const u32x4 q, float (&f)[8]) { f[0] = bflo(q.x); f[1] = bfhi(q.x); f[2] = bflo(q.y); f[3] = bfhi(q.y); f[4] = bflo(q.z); f[5] = bfhi(q.z); f[6] = bflo(q.w); f[7] = bfhi(q.w); }
; __device__ __forceinline__ void pool_chunk(PCP p, int chunk, int tid) {
;     ...
;         for (int k = 1; k < 16; ++k) { if (k < w && k <= pos0) { const u32x4 zw = *(const u32x4*)(proj + (size_t)(t0 - k) * 1536 + c); float q[8]; UNPACK8(zw, q);
; #pragma unroll
;             for (int e = 0; e < 8; ++e) s[e] += q[e]; } }
.LBB0_339:
	v_add_u32_e32 v5, -13, v4
	v_mad_i64_i32 v[54:55], s[28:29], v5, s45, v[8:9]
	v_mov_b32_e32 v54, v132
	v_mov_b32_e32 v55, v133
	v_mov_b32_e32 v56, v134
	v_mov_b32_e32 v57, v135
	v_lshlrev_b32_e32 v58, 16, v54
	v_and_b32_e32 v59, 0xffff0000, v54
	v_lshlrev_b32_e32 v54, 16, v55
	v_and_b32_e32 v55, 0xffff0000, v55
	v_pk_add_f32 v[2:3], v[2:3], v[54:55]
	v_lshlrev_b32_e32 v54, 16, v56
	v_and_b32_e32 v55, 0xffff0000, v56
	v_pk_add_f32 v[6:7], v[6:7], v[54:55]
	v_lshlrev_b32_e32 v54, 16, v57
	v_and_b32_e32 v55, 0xffff0000, v57
	v_pk_add_f32 v[0:1], v[0:1], v[58:59]
	v_pk_add_f32 v[52:53], v[52:53], v[54:55]
	s_or_b64 exec, exec, s[16:17]
	s_and_saveexec_b64 s[16:17], s[4:5]
	s_cbranch_execnz .LBB0_420

; __device__ __forceinline__ unsigned cvt_pk_bf16(float lo, float hi) { unsigned r; asm volatile("v_cvt_pk_bf16_f32 %0, %1, %2" : "=v"(r) : "v"(lo), "v"(hi)); return r; }
; __device__ __forceinline__ void UNPACK8(const u32x4 q, float (&f)[8]) { f[0] = bflo(q.x); f[1] = bfhi(q.x); f[2] = bflo(q.y); f[3] = bfhi(q.y); f[4] = bflo(q.z); f[5] = bfhi(q.z); f[6] = bflo(q.w); f[7] = bfhi(q.w); }
; __device__ __forceinline__ void pool_chunk(PCP p, int chunk, int tid) {
;     ...
;         for (int k = 1; k < 16; ++k) { if (k < w && k <= pos0) { const u32x4 zw = *(const u32x4*)(proj + (size_t)(t0 - k) * 1536 + c); float q[8]; UNPACK8(zw, q);
; #pragma unroll
;             for (int e = 0; e < 8; ++e) s[e] += q[e]; } }
; #pragma unroll
;         for (int i = 0; i < 16; ++i) { const int t = t0 + i, pos = pos0 + i;
;             const u32x4 zw = *(const u32x4*)(proj + (size_t)t * 1536 + c); float z[8]; UNPACK8(zw, z);
; #pragma unroll
;             for (int e = 0; e < 8; ++e) s[e] += z[e];
;             const int cnt = (pos + 1 < w) ? pos + 1 : w; const float inv = 1.0f / (float)cnt;
;             u32x4 o; o.x = cvt_pk_bf16(s[0] * inv - z[0], s[1] * inv - z[1]); o.y = cvt_pk_bf16(s[2] * inv - z[2], s[3] * inv - z[3]); o.z = cvt_pk_bf16(s[4] * inv - z[4], s[5] * inv - z[5]); o.w = cvt_pk_bf16(s[6] * inv - z[6], s[7] * inv - z[7]);
;             *(u32x4*)(pooled + (size_t)t * 512 + c) = o;
;             if (pos + 1 >= w) { const u32x4 ow = *(const u32x4*)(proj + (size_t)(t + 1 - w) * 1536 + c); float q[8]; UNPACK8(ow, q);
; #pragma unroll
;                 for (int e = 0; e < 8; ++e) s[e] -= q[e]; } }
.LBB0_341:
	v_add_u32_e32 v5, -15, v4
	v_mad_i64_i32 v[54:55], s[4:5], v5, s45, v[8:9]
	v_mov_b32_e32 v54, v140
	v_mov_b32_e32 v55, v141
	v_mov_b32_e32 v56, v142
	v_mov_b32_e32 v57, v143
	v_lshlrev_b32_e32 v58, 16, v54
	v_and_b32_e32 v59, 0xffff0000, v54
	v_lshlrev_b32_e32 v54, 16, v55
	v_and_b32_e32 v55, 0xffff0000, v55
	v_pk_add_f32 v[2:3], v[2:3], v[54:55]
	v_lshlrev_b32_e32 v54, 16, v56
	v_and_b32_e32 v55, 0xffff0000, v56
	v_pk_add_f32 v[6:7], v[6:7], v[54:55]
	v_lshlrev_b32_e32 v54, 16, v57
	v_and_b32_e32 v55, 0xffff0000, v57
	v_pk_add_f32 v[0:1], v[0:1], v[58:59]
	v_pk_add_f32 v[52:53], v[52:53], v[54:55]
.LBB0_342:
	s_or_b64 exec, exec, s[16:17]
	v_sub_u32_e32 v84, v4, v67
	v_add_u32_e32 v84, 1, v84
	v_mad_i64_i32 v[86:87], s[4:5], v84, s45, v[8:9]
	global_load_dwordx4 v[84:87], v[86:87], off
	v_sub_u32_e32 v88, v4, v67
	v_add_u32_e32 v88, 2, v88
	v_mad_i64_i32 v[90:91], s[4:5], v88, s45, v[8:9]
	global_load_dwordx4 v[88:91], v[90:91], off
	v_sub_u32_e32 v92, v4, v67
	v_add_u32_e32 v92, 3, v92
	v_mad_i64_i32 v[94:95], s[4:5], v92, s45, v[8:9]
	global_load_dwordx4 v[92:95], v[94:95], off
	v_sub_u32_e32 v96, v4, v67
	v_add_u32_e32 v96, 4, v96
	v_mad_i64_i32 v[98:99], s[4:5], v96, s45, v[8:9]
	global_load_dwordx4 v[96:99], v[98:99], off
	v_sub_u32_e32 v100, v4, v67
	v_add_u32_e32 v100, 5, v100
	v_mad_i64_i32 v[102:103], s[4:5], v100, s45, v[8:9]
	global_load_dwordx4 v[100:103], v[102:103], off
	v_sub_u32_e32 v104, v4, v67
	v_add_u32_e32 v104, 6, v104
	v_mad_i64_i32 v[106:107], s[4:5], v104, s45, v[8:9]
	global_load_dwordx4 v[104:107], v[106:107], off
	v_sub_u32_e32 v108, v4, v67
	v_add_u32_e32 v108, 7, v108
	v_mad_i64_i32 v[110:111], s[4:5], v108, s45, v[8:9]
	global_load_dwordx4 v[108:111], v[110:111], off
	v_sub_u32_e32 v112, v4, v67
	v_add_u32_e32 v112, 8, v112
	v_mad_i64_i32 v[114:115], s[4:5], v112, s45, v[8:9]
	global_load_dwordx4 v[112:115], v[114:115], off
	v_sub_u32_e32 v116, v4, v67
	v_add_u32_e32 v116, 9, v116
	v_mad_i64_i32 v[118:119], s[4:5], v116, s45, v[8:9]
	global_load_dwordx4 v[116:119], v[118:119], off
	v_sub_u32_e32 v120, v4, v67
	v_add_u32_e32 v120, 10, v120
	v_mad_i64_i32 v[122:123], s[4:5], v120, s45, v[8:9]
	global_load_dwordx4 v[120:123], v[122:123], off
	v_sub_u32_e32 v124, v4, v67
	v_add_u32_e32 v124, 11, v124
	v_mad_i64_i32 v[126:127], s[4:5], v124, s45, v[8:9]
	global_load_dwordx4 v[124:127], v[126:127], off
	v_sub_u32_e32 v128, v4, v67
	v_add_u32_e32 v128, 12, v128
	v_mad_i64_i32 v[130:131], s[4:5], v128, s45, v[8:9]
	global_load_dwordx4 v[128:131], v[130:131], off
	v_sub_u32_e32 v132, v4, v67
	v_add_u32_e32 v132, 13, v132
	v_mad_i64_i32 v[134:135], s[4:5], v132, s45, v[8:9]
	global_load_dwordx4 v[132:135], v[134:135], off
	v_sub_u32_e32 v136, v4, v67
	v_add_u32_e32 v136, 14, v136
	v_mad_i64_i32 v[138:139], s[4:5], v136, s45, v[8:9]
	global_load_dwordx4 v[136:139], v[138:139], off
	v_sub_u32_e32 v140, v4, v67
	v_add_u32_e32 v140, 15, v140
	v_mad_i64_i32 v[142:143], s[4:5], v140, s45, v[8:9]
	global_load_dwordx4 v[140:143], v[142:143], off
	s_waitcnt vmcnt(0)
	v_mad_i64_i32 v[54:55], s[4:5], v4, s45, v[8:9]
	v_mov_b32_e32 v58, v144
	v_mov_b32_e32 v59, v145
	v_mov_b32_e32 v60, v146
	v_mov_b32_e32 v61, v147
	v_or_b32_e32 v64, 1, v77
	v_ashrrev_i32_e32 v5, 31, v4
	v_lshlrev_b32_e32 v62, 16, v58
	v_and_b32_e32 v63, 0xffff0000, v58
	v_pk_add_f32 v[56:57], v[0:1], v[62:63]
	v_min_u32_e32 v0, v64, v67
	v_cvt_f32_ubyte0_e32 v0, v0
	v_div_scale_f32 v1, s[4:5], v0, v0, 1.0
	v_rcp_f32_e32 v65, v1
	v_lshlrev_b32_e32 v58, 16, v59
	v_and_b32_e32 v59, 0xffff0000, v59
	v_pk_add_f32 v[54:55], v[2:3], v[58:59]
	v_fma_f32 v78, -v1, v65, 1.0
	v_fmac_f32_e32 v65, v78, v65
	v_div_scale_f32 v78, vcc, 1.0, v0, 1.0
	v_mul_f32_e32 v79, v78, v65
	v_fma_f32 v80, -v1, v79, v78
	v_fmac_f32_e32 v79, v80, v65
	v_fma_f32 v1, -v1, v79, v78
	v_div_fmas_f32 v1, v1, v65, v79
	v_lshlrev_b32_e32 v2, 16, v60
	v_and_b32_e32 v3, 0xffff0000, v60
	v_div_fixup_f32 v65, v1, v0, 1.0
	v_pk_add_f32 v[6:7], v[6:7], v[2:3]
	v_lshlrev_b32_e32 v60, 16, v61
	v_and_b32_e32 v61, 0xffff0000, v61
	v_fma_f32 v0, v65, v56, -v62
	v_fma_f32 v1, v65, v57, -v63
	v_pk_add_f32 v[52:53], v[52:53], v[60:61]
	v_cvt_pk_bf16_f32 v0, v0, v1
	v_fma_f32 v1, v65, v54, -v58
	v_fma_f32 v58, v65, v55, -v59
	v_fma_f32 v2, v65, v6, -v2
	v_fma_f32 v3, v65, v7, -v3
	v_cvt_pk_bf16_f32 v1, v1, v58
	v_cvt_pk_bf16_f32 v2, v2, v3
	v_fma_f32 v3, v65, v52, -v60
	v_fma_f32 v58, v65, v53, -v61
	v_cvt_pk_bf16_f32 v3, v3, v58
	v_lshlrev_b64 v[58:59], 10, v[4:5]
	v_lshl_add_u64 v[58:59], v[10:11], 0, v[58:59]
	v_cmp_ge_u32_e32 vcc, v64, v67
	global_store_dwordx4 v[58:59], v[0:3], off
	s_and_saveexec_b64 s[4:5], vcc
	s_cbranch_execz .LBB0_344
	v_sub_u32_e32 v0, v4, v67
	v_or_b32_e32 v0, 1, v0
	v_mad_i64_i32 v[0:1], s[16:17], v0, s45, v[8:9]
	v_mov_b32_e32 v0, v84
	v_mov_b32_e32 v1, v85
	v_mov_b32_e32 v2, v86
	v_mov_b32_e32 v3, v87
	v_lshlrev_b32_e32 v58, 16, v0
	v_and_b32_e32 v59, 0xffff0000, v0
	v_lshlrev_b32_e32 v0, 16, v1
	v_and_b32_e32 v1, 0xffff0000, v1
	v_pk_add_f32 v[54:55], v[54:55], v[0:1] neg_lo:[0,1] neg_hi:[0,1]
	v_lshlrev_b32_e32 v0, 16, v2
	v_and_b32_e32 v1, 0xffff0000, v2
	v_pk_add_f32 v[6:7], v[6:7], v[0:1] neg_lo:[0,1] neg_hi:[0,1]
	v_lshlrev_b32_e32 v0, 16, v3
	v_and_b32_e32 v1, 0xffff0000, v3
	v_pk_add_f32 v[56:57], v[56:57], v[58:59] neg_lo:[0,1] neg_hi:[0,1]
	v_pk_add_f32 v[52:53], v[52:53], v[0:1] neg_lo:[0,1] neg_hi:[0,1]
; __device__ __forceinline__ unsigned cvt_pk_bf16(float lo, float hi) { unsigned r; asm volatile("v_cvt_pk_bf16_f32 %0, %1, %2" : "=v"(r) : "v"(lo), "v"(hi)); return r; }
; __device__ __forceinline__ void UNPACK8(const u32x4 q, float (&f)[8]) { f[0] = bflo(q.x); f[1] = bfhi(q.x); f[2] = bflo(q.y); f[3] = bfhi(q.y); f[4] = bflo(q.z); f[5] = bfhi(q.z); f[6] = bflo(q.w); f[7] = bfhi(q.w); }
; __device__ __forceinline__ void pool_chunk(PCP p, int chunk, int tid) {
;     ...
;         for (int i = 0; i < 16; ++i) { const int t = t0 + i, pos = pos0 + i;
;             const u32x4 zw = *(const u32x4*)(proj + (size_t)t * 1536 + c); float z[8]; UNPACK8(zw, z);
; #pragma unroll
;             for (int e = 0; e < 8; ++e) s[e] += z[e];
;             const int cnt = (pos + 1 < w) ? pos + 1 : w; const float inv = 1.0f / (float)cnt;
;             u32x4 o; o.x = cvt_pk_bf16(s[0] * inv - z[0], s[1] * inv - z[1]); o.y = cvt_pk_bf16(s[2] * inv - z[2], s[3] * inv - z[3]); o.z = cvt_pk_bf16(s[4] * inv - z[4], s[5] * inv - z[5]); o.w = cvt_pk_bf16(s[6] * inv - z[6], s[7] * inv - z[7]);
;             *(u32x4*)(pooled + (size_t)t * 512 + c) = o;
;             if (pos + 1 >= w) { const u32x4 ow = *(const u32x4*)(proj + (size_t)(t + 1 - w) * 1536 + c); float q[8]; UNPACK8(ow, q);
; #pragma unroll
;                 for (int e = 0; e < 8; ++e) s[e] -= q[e]; } }
.LBB0_344:
	s_or_b64 exec, exec, s[4:5]
	v_or_b32_e32 v64, 1, v4
	v_mad_i64_i32 v[0:1], s[4:5], v64, s45, v[8:9]
	v_mov_b32_e32 v0, v148
	v_mov_b32_e32 v1, v149
	v_mov_b32_e32 v2, v150
	v_mov_b32_e32 v3, v151
	v_or_b32_e32 v5, 2, v77
	v_ashrrev_i32_e32 v65, 31, v64
	v_lshlrev_b32_e32 v78, 16, v0
	v_and_b32_e32 v79, 0xffff0000, v0
	v_min_u32_e32 v0, v5, v67
	v_cvt_f32_ubyte0_e32 v0, v0
	v_lshlrev_b32_e32 v80, 16, v1
	v_and_b32_e32 v81, 0xffff0000, v1
	v_div_scale_f32 v1, s[4:5], v0, v0, 1.0
	v_pk_add_f32 v[58:59], v[54:55], v[80:81]
	v_lshlrev_b32_e32 v54, 16, v2
	v_and_b32_e32 v55, 0xffff0000, v2
	v_rcp_f32_e32 v2, v1
	v_pk_add_f32 v[60:61], v[56:57], v[78:79]
	v_pk_add_f32 v[56:57], v[6:7], v[54:55]
	v_lshlrev_b32_e32 v6, 16, v3
	v_and_b32_e32 v7, 0xffff0000, v3
	v_fma_f32 v3, -v1, v2, 1.0
	v_fmac_f32_e32 v2, v3, v2
	v_div_scale_f32 v3, vcc, 1.0, v0, 1.0
	v_pk_add_f32 v[62:63], v[52:53], v[6:7]
	v_mul_f32_e32 v52, v3, v2
	v_fma_f32 v53, -v1, v52, v3
	v_fmac_f32_e32 v52, v53, v2
	v_fma_f32 v1, -v1, v52, v3
	v_div_fmas_f32 v1, v1, v2, v52
	v_div_fixup_f32 v3, v1, v0, 1.0
	v_fma_f32 v0, v3, v60, -v78
	v_fma_f32 v1, v3, v61, -v79
	v_cvt_pk_bf16_f32 v0, v0, v1
	v_fma_f32 v1, v3, v58, -v80
	v_fma_f32 v2, v3, v59, -v81
	v_cvt_pk_bf16_f32 v1, v1, v2
	v_fma_f32 v2, v3, v56, -v54
	v_fma_f32 v52, v3, v57, -v55
	v_fma_f32 v6, v3, v62, -v6
	v_fma_f32 v3, v3, v63, -v7
	v_cvt_pk_bf16_f32 v2, v2, v52
	v_cvt_pk_bf16_f32 v3, v6, v3
	v_lshlrev_b64 v[6:7], 10, v[64:65]
	v_lshl_add_u64 v[6:7], v[10:11], 0, v[6:7]
	v_cmp_ge_u32_e32 vcc, v5, v67
	global_store_dwordx4 v[6:7], v[0:3], off
	s_and_saveexec_b64 s[4:5], vcc
	s_cbranch_execz .LBB0_346
	v_sub_u32_e32 v0, v64, v67
	v_add_u32_e32 v0, 1, v0
	v_mad_i64_i32 v[0:1], s[16:17], v0, s45, v[8:9]
	v_mov_b32_e32 v0, v88
	v_mov_b32_e32 v1, v89
	v_mov_b32_e32 v2, v90
	v_mov_b32_e32 v3, v91
	v_lshlrev_b32_e32 v6, 16, v0
	v_and_b32_e32 v7, 0xffff0000, v0
	v_lshlrev_b32_e32 v0, 16, v1
	v_and_b32_e32 v1, 0xffff0000, v1
	v_pk_add_f32 v[58:59], v[58:59], v[0:1] neg_lo:[0,1] neg_hi:[0,1]
	v_lshlrev_b32_e32 v0, 16, v2
	v_and_b32_e32 v1, 0xffff0000, v2
	v_pk_add_f32 v[56:57], v[56:57], v[0:1] neg_lo:[0,1] neg_hi:[0,1]
	v_lshlrev_b32_e32 v0, 16, v3
	v_and_b32_e32 v1, 0xffff0000, v3
	v_pk_add_f32 v[60:61], v[60:61], v[6:7] neg_lo:[0,1] neg_hi:[0,1]
	v_pk_add_f32 v[62:63], v[62:63], v[0:1] neg_lo:[0,1] neg_hi:[0,1]
.LBB0_346:
	s_or_b64 exec, exec, s[4:5]
	v_or_b32_e32 v64, 2, v4
	v_mad_i64_i32 v[0:1], s[4:5], v64, s45, v[8:9]
	v_mov_b32_e32 v0, v152
	v_mov_b32_e32 v1, v153
	v_mov_b32_e32 v2, v154
	v_mov_b32_e32 v3, v155
	v_or_b32_e32 v5, 3, v77
	v_ashrrev_i32_e32 v65, 31, v64
	v_lshlrev_b32_e32 v78, 16, v0
	v_and_b32_e32 v79, 0xffff0000, v0
	v_min_u32_e32 v0, v5, v67
	v_cvt_f32_ubyte0_e32 v0, v0
	v_pk_add_f32 v[54:55], v[60:61], v[78:79]
	v_lshlrev_b32_e32 v60, 16, v1
	v_and_b32_e32 v61, 0xffff0000, v1
	v_div_scale_f32 v1, s[4:5], v0, v0, 1.0
	v_pk_add_f32 v[6:7], v[58:59], v[60:61]
	v_lshlrev_b32_e32 v58, 16, v2
	v_and_b32_e32 v59, 0xffff0000, v2
	v_rcp_f32_e32 v2, v1
	v_lshlrev_b32_e32 v80, 16, v3
	v_and_b32_e32 v81, 0xffff0000, v3
	v_pk_add_f32 v[52:53], v[56:57], v[58:59]
	v_fma_f32 v3, -v1, v2, 1.0
	v_fmac_f32_e32 v2, v3, v2
	v_div_scale_f32 v3, vcc, 1.0, v0, 1.0
	v_pk_add_f32 v[56:57], v[62:63], v[80:81]
	v_mul_f32_e32 v62, v3, v2
	v_fma_f32 v63, -v1, v62, v3
	v_fmac_f32_e32 v62, v63, v2
	v_fma_f32 v1, -v1, v62, v3
	v_div_fmas_f32 v1, v1, v2, v62
	v_div_fixup_f32 v3, v1, v0, 1.0
	v_fma_f32 v0, v3, v54, -v78
	v_fma_f32 v1, v3, v55, -v79
	v_cvt_pk_bf16_f32 v0, v0, v1
	v_fma_f32 v1, v3, v6, -v60
	v_fma_f32 v2, v3, v7, -v61
	v_cvt_pk_bf16_f32 v1, v1, v2
	v_fma_f32 v2, v3, v52, -v58
	v_fma_f32 v58, v3, v53, -v59
	v_cvt_pk_bf16_f32 v2, v2, v58
	v_fma_f32 v58, v3, v56, -v80
	v_fma_f32 v3, v3, v57, -v81
	v_cvt_pk_bf16_f32 v3, v58, v3
	v_lshlrev_b64 v[58:59], 10, v[64:65]
	v_lshl_add_u64 v[58:59], v[10:11], 0, v[58:59]
	v_cmp_ge_u32_e32 vcc, v5, v67
	global_store_dwordx4 v[58:59], v[0:3], off
	s_and_saveexec_b64 s[4:5], vcc
	s_cbranch_execz .LBB0_348
	v_sub_u32_e32 v0, v64, v67
	v_or_b32_e32 v0, 1, v0
	v_mad_i64_i32 v[0:1], s[16:17], v0, s45, v[8:9]
	v_mov_b32_e32 v0, v92
	v_mov_b32_e32 v1, v93
	v_mov_b32_e32 v2, v94
	v_mov_b32_e32 v3, v95
	v_lshlrev_b32_e32 v58, 16, v0
	v_and_b32_e32 v59, 0xffff0000, v0
	v_lshlrev_b32_e32 v0, 16, v1
	v_and_b32_e32 v1, 0xffff0000, v1
	v_pk_add_f32 v[6:7], v[6:7], v[0:1] neg_lo:[0,1] neg_hi:[0,1]
	v_lshlrev_b32_e32 v0, 16, v2
	v_and_b32_e32 v1, 0xffff0000, v2
	v_pk_add_f32 v[52:53], v[52:53], v[0:1] neg_lo:[0,1] neg_hi:[0,1]
	v_lshlrev_b32_e32 v0, 16, v3
	v_and_b32_e32 v1, 0xffff0000, v3
	v_pk_add_f32 v[54:55], v[54:55], v[58:59] neg_lo:[0,1] neg_hi:[0,1]
	v_pk_add_f32 v[56:57], v[56:57], v[0:1] neg_lo:[0,1] neg_hi:[0,1]
; __device__ __forceinline__ unsigned cvt_pk_bf16(float lo, float hi) { unsigned r; asm volatile("v_cvt_pk_bf16_f32 %0, %1, %2" : "=v"(r) : "v"(lo), "v"(hi)); return r; }
; __device__ __forceinline__ void UNPACK8(const u32x4 q, float (&f)[8]) { f[0] = bflo(q.x); f[1] = bfhi(q.x); f[2] = bflo(q.y); f[3] = bfhi(q.y); f[4] = bflo(q.z); f[5] = bfhi(q.z); f[6] = bflo(q.w); f[7] = bfhi(q.w); }
; __device__ __forceinline__ void pool_chunk(PCP p, int chunk, int tid) {
;     ...
;         for (int i = 0; i < 16; ++i) { const int t = t0 + i, pos = pos0 + i;
;             const u32x4 zw = *(const u32x4*)(proj + (size_t)t * 1536 + c); float z[8]; UNPACK8(zw, z);
; #pragma unroll
;             for (int e = 0; e < 8; ++e) s[e] += z[e];
;             const int cnt = (pos + 1 < w) ? pos + 1 : w; const float inv = 1.0f / (float)cnt;
;             u32x4 o; o.x = cvt_pk_bf16(s[0] * inv - z[0], s[1] * inv - z[1]); o.y = cvt_pk_bf16(s[2] * inv - z[2], s[3] * inv - z[3]); o.z = cvt_pk_bf16(s[4] * inv - z[4], s[5] * inv - z[5]); o.w = cvt_pk_bf16(s[6] * inv - z[6], s[7] * inv - z[7]);
;             *(u32x4*)(pooled + (size_t)t * 512 + c) = o;
;             if (pos + 1 >= w) { const u32x4 ow = *(const u32x4*)(proj + (size_t)(t + 1 - w) * 1536 + c); float q[8]; UNPACK8(ow, q);
; #pragma unroll
;                 for (int e = 0; e < 8; ++e) s[e] -= q[e]; } }
.LBB0_348:
	s_or_b64 exec, exec, s[4:5]
	v_or_b32_e32 v58, 3, v4
	v_mad_i64_i32 v[0:1], s[4:5], v58, s45, v[8:9]
	v_mov_b32_e32 v0, v156
	v_mov_b32_e32 v1, v157
	v_mov_b32_e32 v2, v158
	v_mov_b32_e32 v3, v159
	v_or_b32_e32 v5, 4, v77
	v_ashrrev_i32_e32 v59, 31, v58
	v_lshlrev_b32_e32 v60, 16, v0
	v_and_b32_e32 v61, 0xffff0000, v0
	v_min_u32_e32 v0, v5, v67
	v_cvt_f32_ubyte0_e32 v0, v0
	v_lshlrev_b32_e32 v62, 16, v1
	v_and_b32_e32 v63, 0xffff0000, v1
	v_div_scale_f32 v1, s[4:5], v0, v0, 1.0
	v_lshlrev_b32_e32 v64, 16, v2
	v_and_b32_e32 v65, 0xffff0000, v2
	v_rcp_f32_e32 v2, v1
	v_lshlrev_b32_e32 v78, 16, v3
	v_and_b32_e32 v79, 0xffff0000, v3
	v_pk_add_f32 v[54:55], v[54:55], v[60:61]
	v_fma_f32 v3, -v1, v2, 1.0
	v_fmac_f32_e32 v2, v3, v2
	v_div_scale_f32 v3, vcc, 1.0, v0, 1.0
	v_mul_f32_e32 v80, v3, v2
	v_fma_f32 v81, -v1, v80, v3
	v_fmac_f32_e32 v80, v81, v2
	v_fma_f32 v1, -v1, v80, v3
	v_div_fmas_f32 v1, v1, v2, v80
	v_div_fixup_f32 v3, v1, v0, 1.0
	v_pk_add_f32 v[6:7], v[6:7], v[62:63]
	v_fma_f32 v0, v3, v54, -v60
	v_fma_f32 v1, v3, v55, -v61
	v_pk_add_f32 v[52:53], v[52:53], v[64:65]
	v_cvt_pk_bf16_f32 v0, v0, v1
	v_fma_f32 v1, v3, v6, -v62
	v_fma_f32 v2, v3, v7, -v63
	v_pk_add_f32 v[56:57], v[56:57], v[78:79]
	v_cvt_pk_bf16_f32 v1, v1, v2
	v_fma_f32 v2, v3, v52, -v64
	v_fma_f32 v60, v3, v53, -v65
	v_cvt_pk_bf16_f32 v2, v2, v60
	v_fma_f32 v60, v3, v56, -v78
	v_fma_f32 v3, v3, v57, -v79
	v_cvt_pk_bf16_f32 v3, v60, v3
	v_lshlrev_b64 v[60:61], 10, v[58:59]
	v_lshl_add_u64 v[60:61], v[10:11], 0, v[60:61]
	v_cmp_ge_u32_e32 vcc, v5, v67
	global_store_dwordx4 v[60:61], v[0:3], off
	s_and_saveexec_b64 s[4:5], vcc
	s_cbranch_execz .LBB0_350
	v_sub_u32_e32 v0, v58, v67
	v_add_u32_e32 v0, 1, v0
	v_mad_i64_i32 v[0:1], s[16:17], v0, s45, v[8:9]
	v_mov_b32_e32 v0, v96
	v_mov_b32_e32 v1, v97
	v_mov_b32_e32 v2, v98
	v_mov_b32_e32 v3, v99
	v_lshlrev_b32_e32 v58, 16, v0
	v_and_b32_e32 v59, 0xffff0000, v0
	v_lshlrev_b32_e32 v0, 16, v1
	v_and_b32_e32 v1, 0xffff0000, v1
	v_pk_add_f32 v[6:7], v[6:7], v[0:1] neg_lo:[0,1] neg_hi:[0,1]
	v_lshlrev_b32_e32 v0, 16, v2
	v_and_b32_e32 v1, 0xffff0000, v2
	v_pk_add_f32 v[52:53], v[52:53], v[0:1] neg_lo:[0,1] neg_hi:[0,1]
	v_lshlrev_b32_e32 v0, 16, v3
	v_and_b32_e32 v1, 0xffff0000, v3
	v_pk_add_f32 v[54:55], v[54:55], v[58:59] neg_lo:[0,1] neg_hi:[0,1]
	v_pk_add_f32 v[56:57], v[56:57], v[0:1] neg_lo:[0,1] neg_hi:[0,1]
.LBB0_350:
	s_or_b64 exec, exec, s[4:5]
	v_or_b32_e32 v58, 4, v4
	v_mad_i64_i32 v[0:1], s[4:5], v58, s45, v[8:9]
	v_mov_b32_e32 v0, v166
	v_mov_b32_e32 v1, v167
	v_mov_b32_e32 v2, v168
	v_mov_b32_e32 v3, v169
	v_or_b32_e32 v5, 5, v77
	v_ashrrev_i32_e32 v59, 31, v58
	v_lshlrev_b32_e32 v60, 16, v0
	v_and_b32_e32 v61, 0xffff0000, v0
	v_min_u32_e32 v0, v5, v67
	v_cvt_f32_ubyte0_e32 v0, v0
	v_lshlrev_b32_e32 v62, 16, v1
	v_and_b32_e32 v63, 0xffff0000, v1
	v_div_scale_f32 v1, s[4:5], v0, v0, 1.0
	v_lshlrev_b32_e32 v64, 16, v2
	v_and_b32_e32 v65, 0xffff0000, v2
	v_rcp_f32_e32 v2, v1
	v_lshlrev_b32_e32 v78, 16, v3
	v_and_b32_e32 v79, 0xffff0000, v3
	v_pk_add_f32 v[54:55], v[54:55], v[60:61]
	v_fma_f32 v3, -v1, v2, 1.0
	v_fmac_f32_e32 v2, v3, v2
	v_div_scale_f32 v3, vcc, 1.0, v0, 1.0
	v_mul_f32_e32 v80, v3, v2
	v_fma_f32 v81, -v1, v80, v3
	v_fmac_f32_e32 v80, v81, v2
	v_fma_f32 v1, -v1, v80, v3
	v_div_fmas_f32 v1, v1, v2, v80
	v_div_fixup_f32 v3, v1, v0, 1.0
	v_pk_add_f32 v[6:7], v[6:7], v[62:63]
	v_fma_f32 v0, v3, v54, -v60
	v_fma_f32 v1, v3, v55, -v61
	v_pk_add_f32 v[52:53], v[52:53], v[64:65]
	v_cvt_pk_bf16_f32 v0, v0, v1
	v_fma_f32 v1, v3, v6, -v62
	v_fma_f32 v2, v3, v7, -v63
	v_pk_add_f32 v[56:57], v[56:57], v[78:79]
	v_cvt_pk_bf16_f32 v1, v1, v2
	v_fma_f32 v2, v3, v52, -v64
	v_fma_f32 v60, v3, v53, -v65
	v_cvt_pk_bf16_f32 v2, v2, v60
	v_fma_f32 v60, v3, v56, -v78
	v_fma_f32 v3, v3, v57, -v79
	v_cvt_pk_bf16_f32 v3, v60, v3
	v_lshlrev_b64 v[60:61], 10, v[58:59]
	v_lshl_add_u64 v[60:61], v[10:11], 0, v[60:61]
	v_cmp_ge_u32_e32 vcc, v5, v67
	global_store_dwordx4 v[60:61], v[0:3], off
	s_and_saveexec_b64 s[4:5], vcc
	s_cbranch_execz .LBB0_352
	v_sub_u32_e32 v0, v58, v67
	v_or_b32_e32 v0, 1, v0
	v_mad_i64_i32 v[0:1], s[16:17], v0, s45, v[8:9]
	v_mov_b32_e32 v0, v100
	v_mov_b32_e32 v1, v101
	v_mov_b32_e32 v2, v102
	v_mov_b32_e32 v3, v103
	v_lshlrev_b32_e32 v58, 16, v0
	v_and_b32_e32 v59, 0xffff0000, v0
	v_lshlrev_b32_e32 v0, 16, v1
	v_and_b32_e32 v1, 0xffff0000, v1
	v_pk_add_f32 v[6:7], v[6:7], v[0:1] neg_lo:[0,1] neg_hi:[0,1]
	v_lshlrev_b32_e32 v0, 16, v2
	v_and_b32_e32 v1, 0xffff0000, v2
	v_pk_add_f32 v[52:53], v[52:53], v[0:1] neg_lo:[0,1] neg_hi:[0,1]
	v_lshlrev_b32_e32 v0, 16, v3
	v_and_b32_e32 v1, 0xffff0000, v3
	v_pk_add_f32 v[54:55], v[54:55], v[58:59] neg_lo:[0,1] neg_hi:[0,1]
	v_pk_add_f32 v[56:57], v[56:57], v[0:1] neg_lo:[0,1] neg_hi:[0,1]
; __device__ __forceinline__ unsigned cvt_pk_bf16(float lo, float hi) { unsigned r; asm volatile("v_cvt_pk_bf16_f32 %0, %1, %2" : "=v"(r) : "v"(lo), "v"(hi)); return r; }
; __device__ __forceinline__ void UNPACK8(const u32x4 q, float (&f)[8]) { f[0] = bflo(q.x); f[1] = bfhi(q.x); f[2] = bflo(q.y); f[3] = bfhi(q.y); f[4] = bflo(q.z); f[5] = bfhi(q.z); f[6] = bflo(q.w); f[7] = bfhi(q.w); }
; __device__ __forceinline__ void pool_chunk(PCP p, int chunk, int tid) {
;     ...
;         for (int i = 0; i < 16; ++i) { const int t = t0 + i, pos = pos0 + i;
;             const u32x4 zw = *(const u32x4*)(proj + (size_t)t * 1536 + c); float z[8]; UNPACK8(zw, z);
; #pragma unroll
;             for (int e = 0; e < 8; ++e) s[e] += z[e];
;             const int cnt = (pos + 1 < w) ? pos + 1 : w; const float inv = 1.0f / (float)cnt;
;             u32x4 o; o.x = cvt_pk_bf16(s[0] * inv - z[0], s[1] * inv - z[1]); o.y = cvt_pk_bf16(s[2] * inv - z[2], s[3] * inv - z[3]); o.z = cvt_pk_bf16(s[4] * inv - z[4], s[5] * inv - z[5]); o.w = cvt_pk_bf16(s[6] * inv - z[6], s[7] * inv - z[7]);
;             *(u32x4*)(pooled + (size_t)t * 512 + c) = o;
;             if (pos + 1 >= w) { const u32x4 ow = *(const u32x4*)(proj + (size_t)(t + 1 - w) * 1536 + c); float q[8]; UNPACK8(ow, q);
; #pragma unroll
;                 for (int e = 0; e < 8; ++e) s[e] -= q[e]; } }
.LBB0_352:
	s_or_b64 exec, exec, s[4:5]
	v_or_b32_e32 v58, 5, v4
	v_mad_i64_i32 v[0:1], s[4:5], v58, s45, v[8:9]
	v_mov_b32_e32 v0, v178
	v_mov_b32_e32 v1, v179
	v_mov_b32_e32 v2, v180
	v_mov_b32_e32 v3, v181
	v_or_b32_e32 v5, 6, v77
	v_ashrrev_i32_e32 v59, 31, v58
	v_lshlrev_b32_e32 v60, 16, v0
	v_and_b32_e32 v61, 0xffff0000, v0
	v_min_u32_e32 v0, v5, v67
	v_cvt_f32_ubyte0_e32 v0, v0
	v_lshlrev_b32_e32 v62, 16, v1
	v_and_b32_e32 v63, 0xffff0000, v1
	v_div_scale_f32 v1, s[4:5], v0, v0, 1.0
	v_lshlrev_b32_e32 v64, 16, v2
	v_and_b32_e32 v65, 0xffff0000, v2
	v_rcp_f32_e32 v2, v1
	v_lshlrev_b32_e32 v78, 16, v3
	v_and_b32_e32 v79, 0xffff0000, v3
	v_pk_add_f32 v[54:55], v[54:55], v[60:61]
	v_fma_f32 v3, -v1, v2, 1.0
	v_fmac_f32_e32 v2, v3, v2
	v_div_scale_f32 v3, vcc, 1.0, v0, 1.0
	v_mul_f32_e32 v80, v3, v2
	v_fma_f32 v81, -v1, v80, v3
	v_fmac_f32_e32 v80, v81, v2
	v_fma_f32 v1, -v1, v80, v3
	v_div_fmas_f32 v1, v1, v2, v80
	v_div_fixup_f32 v3, v1, v0, 1.0
	v_pk_add_f32 v[6:7], v[6:7], v[62:63]
	v_fma_f32 v0, v3, v54, -v60
	v_fma_f32 v1, v3, v55, -v61
	v_pk_add_f32 v[52:53], v[52:53], v[64:65]
	v_cvt_pk_bf16_f32 v0, v0, v1
	v_fma_f32 v1, v3, v6, -v62
	v_fma_f32 v2, v3, v7, -v63
	v_pk_add_f32 v[56:57], v[56:57], v[78:79]
	v_cvt_pk_bf16_f32 v1, v1, v2
	v_fma_f32 v2, v3, v52, -v64
	v_fma_f32 v60, v3, v53, -v65
	v_cvt_pk_bf16_f32 v2, v2, v60
	v_fma_f32 v60, v3, v56, -v78
	v_fma_f32 v3, v3, v57, -v79
	v_cvt_pk_bf16_f32 v3, v60, v3
	v_lshlrev_b64 v[60:61], 10, v[58:59]
	v_lshl_add_u64 v[60:61], v[10:11], 0, v[60:61]
	v_cmp_ge_u32_e32 vcc, v5, v67
	global_store_dwordx4 v[60:61], v[0:3], off
	s_and_saveexec_b64 s[4:5], vcc
	s_cbranch_execz .LBB0_354
	v_sub_u32_e32 v0, v58, v67
	v_add_u32_e32 v0, 1, v0
	v_mad_i64_i32 v[0:1], s[16:17], v0, s45, v[8:9]
	v_mov_b32_e32 v0, v104
	v_mov_b32_e32 v1, v105
	v_mov_b32_e32 v2, v106
	v_mov_b32_e32 v3, v107
	v_lshlrev_b32_e32 v58, 16, v0
	v_and_b32_e32 v59, 0xffff0000, v0
	v_lshlrev_b32_e32 v0, 16, v1
	v_and_b32_e32 v1, 0xffff0000, v1
	v_pk_add_f32 v[6:7], v[6:7], v[0:1] neg_lo:[0,1] neg_hi:[0,1]
	v_lshlrev_b32_e32 v0, 16, v2
	v_and_b32_e32 v1, 0xffff0000, v2
	v_pk_add_f32 v[52:53], v[52:53], v[0:1] neg_lo:[0,1] neg_hi:[0,1]
	v_lshlrev_b32_e32 v0, 16, v3
	v_and_b32_e32 v1, 0xffff0000, v3
	v_pk_add_f32 v[54:55], v[54:55], v[58:59] neg_lo:[0,1] neg_hi:[0,1]
	v_pk_add_f32 v[56:57], v[56:57], v[0:1] neg_lo:[0,1] neg_hi:[0,1]
.LBB0_354:
	s_or_b64 exec, exec, s[4:5]
	v_or_b32_e32 v58, 6, v4
	v_mad_i64_i32 v[0:1], s[4:5], v58, s45, v[8:9]
	v_mov_b32_e32 v0, v182
	v_mov_b32_e32 v1, v183
	v_mov_b32_e32 v2, v184
	v_mov_b32_e32 v3, v185
	v_or_b32_e32 v5, 7, v77
	v_ashrrev_i32_e32 v59, 31, v58
	v_lshlrev_b32_e32 v60, 16, v0
	v_and_b32_e32 v61, 0xffff0000, v0
	v_min_u32_e32 v0, v5, v67
	v_cvt_f32_ubyte0_e32 v0, v0
	v_lshlrev_b32_e32 v62, 16, v1
	v_and_b32_e32 v63, 0xffff0000, v1
	v_div_scale_f32 v1, s[4:5], v0, v0, 1.0
	v_lshlrev_b32_e32 v64, 16, v2
	v_and_b32_e32 v65, 0xffff0000, v2
	v_rcp_f32_e32 v2, v1
	v_lshlrev_b32_e32 v78, 16, v3
	v_and_b32_e32 v79, 0xffff0000, v3
	v_pk_add_f32 v[54:55], v[54:55], v[60:61]
	v_fma_f32 v3, -v1, v2, 1.0
	v_fmac_f32_e32 v2, v3, v2
	v_div_scale_f32 v3, vcc, 1.0, v0, 1.0
	v_mul_f32_e32 v80, v3, v2
	v_fma_f32 v81, -v1, v80, v3
	v_fmac_f32_e32 v80, v81, v2
	v_fma_f32 v1, -v1, v80, v3
	v_div_fmas_f32 v1, v1, v2, v80
	v_div_fixup_f32 v3, v1, v0, 1.0
	v_pk_add_f32 v[6:7], v[6:7], v[62:63]
	v_fma_f32 v0, v3, v54, -v60
	v_fma_f32 v1, v3, v55, -v61
	v_pk_add_f32 v[52:53], v[52:53], v[64:65]
	v_cvt_pk_bf16_f32 v0, v0, v1
	v_fma_f32 v1, v3, v6, -v62
	v_fma_f32 v2, v3, v7, -v63
	v_pk_add_f32 v[56:57], v[56:57], v[78:79]
	v_cvt_pk_bf16_f32 v1, v1, v2
	v_fma_f32 v2, v3, v52, -v64
	v_fma_f32 v60, v3, v53, -v65
	v_cvt_pk_bf16_f32 v2, v2, v60
	v_fma_f32 v60, v3, v56, -v78
	v_fma_f32 v3, v3, v57, -v79
	v_cvt_pk_bf16_f32 v3, v60, v3
	v_lshlrev_b64 v[60:61], 10, v[58:59]
	v_lshl_add_u64 v[60:61], v[10:11], 0, v[60:61]
	v_cmp_ge_u32_e32 vcc, v5, v67
	global_store_dwordx4 v[60:61], v[0:3], off
	s_and_saveexec_b64 s[4:5], vcc
	s_cbranch_execz .LBB0_356
	v_sub_u32_e32 v0, v58, v67
	v_or_b32_e32 v0, 1, v0
	v_mad_i64_i32 v[0:1], s[16:17], v0, s45, v[8:9]
	v_mov_b32_e32 v0, v108
	v_mov_b32_e32 v1, v109
	v_mov_b32_e32 v2, v110
	v_mov_b32_e32 v3, v111
	v_lshlrev_b32_e32 v58, 16, v0
	v_and_b32_e32 v59, 0xffff0000, v0
	v_lshlrev_b32_e32 v0, 16, v1
	v_and_b32_e32 v1, 0xffff0000, v1
	v_pk_add_f32 v[6:7], v[6:7], v[0:1] neg_lo:[0,1] neg_hi:[0,1]
	v_lshlrev_b32_e32 v0, 16, v2
	v_and_b32_e32 v1, 0xffff0000, v2
	v_pk_add_f32 v[52:53], v[52:53], v[0:1] neg_lo:[0,1] neg_hi:[0,1]
	v_lshlrev_b32_e32 v0, 16, v3
	v_and_b32_e32 v1, 0xffff0000, v3
	v_pk_add_f32 v[54:55], v[54:55], v[58:59] neg_lo:[0,1] neg_hi:[0,1]
	v_pk_add_f32 v[56:57], v[56:57], v[0:1] neg_lo:[0,1] neg_hi:[0,1]
; __device__ __forceinline__ unsigned cvt_pk_bf16(float lo, float hi) { unsigned r; asm volatile("v_cvt_pk_bf16_f32 %0, %1, %2" : "=v"(r) : "v"(lo), "v"(hi)); return r; }
; __device__ __forceinline__ void UNPACK8(const u32x4 q, float (&f)[8]) { f[0] = bflo(q.x); f[1] = bfhi(q.x); f[2] = bflo(q.y); f[3] = bfhi(q.y); f[4] = bflo(q.z); f[5] = bfhi(q.z); f[6] = bflo(q.w); f[7] = bfhi(q.w); }
; __device__ __forceinline__ void pool_chunk(PCP p, int chunk, int tid) {
;     ...
;         for (int i = 0; i < 16; ++i) { const int t = t0 + i, pos = pos0 + i;
;             const u32x4 zw = *(const u32x4*)(proj + (size_t)t * 1536 + c); float z[8]; UNPACK8(zw, z);
; #pragma unroll
;             for (int e = 0; e < 8; ++e) s[e] += z[e];
;             const int cnt = (pos + 1 < w) ? pos + 1 : w; const float inv = 1.0f / (float)cnt;
;             u32x4 o; o.x = cvt_pk_bf16(s[0] * inv - z[0], s[1] * inv - z[1]); o.y = cvt_pk_bf16(s[2] * inv - z[2], s[3] * inv - z[3]); o.z = cvt_pk_bf16(s[4] * inv - z[4], s[5] * inv - z[5]); o.w = cvt_pk_bf16(s[6] * inv - z[6], s[7] * inv - z[7]);
;             *(u32x4*)(pooled + (size_t)t * 512 + c) = o;
;             if (pos + 1 >= w) { const u32x4 ow = *(const u32x4*)(proj + (size_t)(t + 1 - w) * 1536 + c); float q[8]; UNPACK8(ow, q);
; #pragma unroll
;                 for (int e = 0; e < 8; ++e) s[e] -= q[e]; } }
.LBB0_356:
	s_or_b64 exec, exec, s[4:5]
	v_or_b32_e32 v58, 7, v4
	v_mad_i64_i32 v[0:1], s[4:5], v58, s45, v[8:9]
	v_mov_b32_e32 v0, v186
	v_mov_b32_e32 v1, v187
	v_mov_b32_e32 v2, v188
	v_mov_b32_e32 v3, v189
	v_or_b32_e32 v5, 8, v77
	v_ashrrev_i32_e32 v59, 31, v58
	v_lshlrev_b32_e32 v60, 16, v0
	v_and_b32_e32 v61, 0xffff0000, v0
	v_min_u32_e32 v0, v5, v67
	v_cvt_f32_ubyte0_e32 v0, v0
	v_lshlrev_b32_e32 v62, 16, v1
	v_and_b32_e32 v63, 0xffff0000, v1
	v_div_scale_f32 v1, s[4:5], v0, v0, 1.0
	v_lshlrev_b32_e32 v64, 16, v2
	v_and_b32_e32 v65, 0xffff0000, v2
	v_rcp_f32_e32 v2, v1
	v_lshlrev_b32_e32 v78, 16, v3
	v_and_b32_e32 v79, 0xffff0000, v3
	v_pk_add_f32 v[54:55], v[54:55], v[60:61]
	v_fma_f32 v3, -v1, v2, 1.0
	v_fmac_f32_e32 v2, v3, v2
	v_div_scale_f32 v3, vcc, 1.0, v0, 1.0
	v_mul_f32_e32 v80, v3, v2
	v_fma_f32 v81, -v1, v80, v3
	v_fmac_f32_e32 v80, v81, v2
	v_fma_f32 v1, -v1, v80, v3
	v_div_fmas_f32 v1, v1, v2, v80
	v_div_fixup_f32 v3, v1, v0, 1.0
	v_pk_add_f32 v[6:7], v[6:7], v[62:63]
	v_fma_f32 v0, v3, v54, -v60
	v_fma_f32 v1, v3, v55, -v61
	v_pk_add_f32 v[52:53], v[52:53], v[64:65]
	v_cvt_pk_bf16_f32 v0, v0, v1
	v_fma_f32 v1, v3, v6, -v62
	v_fma_f32 v2, v3, v7, -v63
	v_pk_add_f32 v[56:57], v[56:57], v[78:79]
	v_cvt_pk_bf16_f32 v1, v1, v2
	v_fma_f32 v2, v3, v52, -v64
	v_fma_f32 v60, v3, v53, -v65
	v_cvt_pk_bf16_f32 v2, v2, v60
	v_fma_f32 v60, v3, v56, -v78
	v_fma_f32 v3, v3, v57, -v79
	v_cvt_pk_bf16_f32 v3, v60, v3
	v_lshlrev_b64 v[60:61], 10, v[58:59]
	v_lshl_add_u64 v[60:61], v[10:11], 0, v[60:61]
	v_cmp_ge_u32_e32 vcc, v5, v67
	global_store_dwordx4 v[60:61], v[0:3], off
	s_and_saveexec_b64 s[4:5], vcc
	s_cbranch_execz .LBB0_358
	v_sub_u32_e32 v0, v58, v67
	v_add_u32_e32 v0, 1, v0
	v_mad_i64_i32 v[0:1], s[16:17], v0, s45, v[8:9]
	v_mov_b32_e32 v0, v112
	v_mov_b32_e32 v1, v113
	v_mov_b32_e32 v2, v114
	v_mov_b32_e32 v3, v115
	v_lshlrev_b32_e32 v58, 16, v0
	v_and_b32_e32 v59, 0xffff0000, v0
	v_lshlrev_b32_e32 v0, 16, v1
	v_and_b32_e32 v1, 0xffff0000, v1
	v_pk_add_f32 v[6:7], v[6:7], v[0:1] neg_lo:[0,1] neg_hi:[0,1]
	v_lshlrev_b32_e32 v0, 16, v2
	v_and_b32_e32 v1, 0xffff0000, v2
	v_pk_add_f32 v[52:53], v[52:53], v[0:1] neg_lo:[0,1] neg_hi:[0,1]
	v_lshlrev_b32_e32 v0, 16, v3
	v_and_b32_e32 v1, 0xffff0000, v3
	v_pk_add_f32 v[54:55], v[54:55], v[58:59] neg_lo:[0,1] neg_hi:[0,1]
	v_pk_add_f32 v[56:57], v[56:57], v[0:1] neg_lo:[0,1] neg_hi:[0,1]
.LBB0_358:
	s_or_b64 exec, exec, s[4:5]
	v_or_b32_e32 v58, 8, v4
	v_mad_i64_i32 v[0:1], s[4:5], v58, s45, v[8:9]
	v_mov_b32_e32 v0, v190
	v_mov_b32_e32 v1, v191
	v_mov_b32_e32 v2, v192
	v_mov_b32_e32 v3, v193
	v_or_b32_e32 v5, 9, v77
	v_ashrrev_i32_e32 v59, 31, v58
	v_lshlrev_b32_e32 v60, 16, v0
	v_and_b32_e32 v61, 0xffff0000, v0
	v_min_u32_e32 v0, v5, v67
	v_cvt_f32_ubyte0_e32 v0, v0
	v_lshlrev_b32_e32 v62, 16, v1
	v_and_b32_e32 v63, 0xffff0000, v1
	v_div_scale_f32 v1, s[4:5], v0, v0, 1.0
	v_lshlrev_b32_e32 v64, 16, v2
	v_and_b32_e32 v65, 0xffff0000, v2
	v_rcp_f32_e32 v2, v1
	v_lshlrev_b32_e32 v78, 16, v3
	v_and_b32_e32 v79, 0xffff0000, v3
	v_pk_add_f32 v[54:55], v[54:55], v[60:61]
	v_fma_f32 v3, -v1, v2, 1.0
	v_fmac_f32_e32 v2, v3, v2
	v_div_scale_f32 v3, vcc, 1.0, v0, 1.0
	v_mul_f32_e32 v80, v3, v2
	v_fma_f32 v81, -v1, v80, v3
	v_fmac_f32_e32 v80, v81, v2
	v_fma_f32 v1, -v1, v80, v3
	v_div_fmas_f32 v1, v1, v2, v80
	v_div_fixup_f32 v3, v1, v0, 1.0
	v_pk_add_f32 v[6:7], v[6:7], v[62:63]
	v_fma_f32 v0, v3, v54, -v60
	v_fma_f32 v1, v3, v55, -v61
	v_pk_add_f32 v[52:53], v[52:53], v[64:65]
	v_cvt_pk_bf16_f32 v0, v0, v1
	v_fma_f32 v1, v3, v6, -v62
	v_fma_f32 v2, v3, v7, -v63
	v_pk_add_f32 v[56:57], v[56:57], v[78:79]
	v_cvt_pk_bf16_f32 v1, v1, v2
	v_fma_f32 v2, v3, v52, -v64
	v_fma_f32 v60, v3, v53, -v65
	v_cvt_pk_bf16_f32 v2, v2, v60
	v_fma_f32 v60, v3, v56, -v78
	v_fma_f32 v3, v3, v57, -v79
	v_cvt_pk_bf16_f32 v3, v60, v3
	v_lshlrev_b64 v[60:61], 10, v[58:59]
	v_lshl_add_u64 v[60:61], v[10:11], 0, v[60:61]
	v_cmp_ge_u32_e32 vcc, v5, v67
	global_store_dwordx4 v[60:61], v[0:3], off
	s_and_saveexec_b64 s[4:5], vcc
	s_cbranch_execz .LBB0_360
	v_sub_u32_e32 v0, v58, v67
	v_or_b32_e32 v0, 1, v0
	v_mad_i64_i32 v[0:1], s[16:17], v0, s45, v[8:9]
	v_mov_b32_e32 v0, v116
	v_mov_b32_e32 v1, v117
	v_mov_b32_e32 v2, v118
	v_mov_b32_e32 v3, v119
	v_lshlrev_b32_e32 v58, 16, v0
	v_and_b32_e32 v59, 0xffff0000, v0
	v_lshlrev_b32_e32 v0, 16, v1
	v_and_b32_e32 v1, 0xffff0000, v1
	v_pk_add_f32 v[6:7], v[6:7], v[0:1] neg_lo:[0,1] neg_hi:[0,1]
	v_lshlrev_b32_e32 v0, 16, v2
	v_and_b32_e32 v1, 0xffff0000, v2
	v_pk_add_f32 v[52:53], v[52:53], v[0:1] neg_lo:[0,1] neg_hi:[0,1]
	v_lshlrev_b32_e32 v0, 16, v3
	v_and_b32_e32 v1, 0xffff0000, v3
	v_pk_add_f32 v[54:55], v[54:55], v[58:59] neg_lo:[0,1] neg_hi:[0,1]
	v_pk_add_f32 v[56:57], v[56:57], v[0:1] neg_lo:[0,1] neg_hi:[0,1]
; __device__ __forceinline__ unsigned cvt_pk_bf16(float lo, float hi) { unsigned r; asm volatile("v_cvt_pk_bf16_f32 %0, %1, %2" : "=v"(r) : "v"(lo), "v"(hi)); return r; }
; __device__ __forceinline__ void UNPACK8(const u32x4 q, float (&f)[8]) { f[0] = bflo(q.x); f[1] = bfhi(q.x); f[2] = bflo(q.y); f[3] = bfhi(q.y); f[4] = bflo(q.z); f[5] = bfhi(q.z); f[6] = bflo(q.w); f[7] = bfhi(q.w); }
; __device__ __forceinline__ void pool_chunk(PCP p, int chunk, int tid) {
;     ...
;         for (int i = 0; i < 16; ++i) { const int t = t0 + i, pos = pos0 + i;
;             const u32x4 zw = *(const u32x4*)(proj + (size_t)t * 1536 + c); float z[8]; UNPACK8(zw, z);
; #pragma unroll
;             for (int e = 0; e < 8; ++e) s[e] += z[e];
;             const int cnt = (pos + 1 < w) ? pos + 1 : w; const float inv = 1.0f / (float)cnt;
;             u32x4 o; o.x = cvt_pk_bf16(s[0] * inv - z[0], s[1] * inv - z[1]); o.y = cvt_pk_bf16(s[2] * inv - z[2], s[3] * inv - z[3]); o.z = cvt_pk_bf16(s[4] * inv - z[4], s[5] * inv - z[5]); o.w = cvt_pk_bf16(s[6] * inv - z[6], s[7] * inv - z[7]);
;             *(u32x4*)(pooled + (size_t)t * 512 + c) = o;
;             if (pos + 1 >= w) { const u32x4 ow = *(const u32x4*)(proj + (size_t)(t + 1 - w) * 1536 + c); float q[8]; UNPACK8(ow, q);
; #pragma unroll
;                 for (int e = 0; e < 8; ++e) s[e] -= q[e]; } }
.LBB0_360:
	s_or_b64 exec, exec, s[4:5]
	v_or_b32_e32 v58, 9, v4
	v_mad_i64_i32 v[0:1], s[4:5], v58, s45, v[8:9]
	v_mov_b32_e32 v0, v194
	v_mov_b32_e32 v1, v195
	v_mov_b32_e32 v2, v196
	v_mov_b32_e32 v3, v197
	v_or_b32_e32 v5, 10, v77
	v_ashrrev_i32_e32 v59, 31, v58
	v_lshlrev_b32_e32 v60, 16, v0
	v_and_b32_e32 v61, 0xffff0000, v0
	v_min_u32_e32 v0, v5, v67
	v_cvt_f32_ubyte0_e32 v0, v0
	v_lshlrev_b32_e32 v62, 16, v1
	v_and_b32_e32 v63, 0xffff0000, v1
	v_div_scale_f32 v1, s[4:5], v0, v0, 1.0
	v_lshlrev_b32_e32 v64, 16, v2
	v_and_b32_e32 v65, 0xffff0000, v2
	v_rcp_f32_e32 v2, v1
	v_lshlrev_b32_e32 v78, 16, v3
	v_and_b32_e32 v79, 0xffff0000, v3
	v_pk_add_f32 v[54:55], v[54:55], v[60:61]
	v_fma_f32 v3, -v1, v2, 1.0
	v_fmac_f32_e32 v2, v3, v2
	v_div_scale_f32 v3, vcc, 1.0, v0, 1.0
	v_mul_f32_e32 v80, v3, v2
	v_fma_f32 v81, -v1, v80, v3
	v_fmac_f32_e32 v80, v81, v2
	v_fma_f32 v1, -v1, v80, v3
	v_div_fmas_f32 v1, v1, v2, v80
	v_div_fixup_f32 v3, v1, v0, 1.0
	v_pk_add_f32 v[6:7], v[6:7], v[62:63]
	v_fma_f32 v0, v3, v54, -v60
	v_fma_f32 v1, v3, v55, -v61
	v_pk_add_f32 v[52:53], v[52:53], v[64:65]
	v_cvt_pk_bf16_f32 v0, v0, v1
	v_fma_f32 v1, v3, v6, -v62
	v_fma_f32 v2, v3, v7, -v63
	v_pk_add_f32 v[56:57], v[56:57], v[78:79]
	v_cvt_pk_bf16_f32 v1, v1, v2
	v_fma_f32 v2, v3, v52, -v64
	v_fma_f32 v60, v3, v53, -v65
	v_cvt_pk_bf16_f32 v2, v2, v60
	v_fma_f32 v60, v3, v56, -v78
	v_fma_f32 v3, v3, v57, -v79
	v_cvt_pk_bf16_f32 v3, v60, v3
	v_lshlrev_b64 v[60:61], 10, v[58:59]
	v_lshl_add_u64 v[60:61], v[10:11], 0, v[60:61]
	v_cmp_ge_u32_e32 vcc, v5, v67
	global_store_dwordx4 v[60:61], v[0:3], off
	s_and_saveexec_b64 s[4:5], vcc
	s_cbranch_execz .LBB0_362
	v_sub_u32_e32 v0, v58, v67
	v_add_u32_e32 v0, 1, v0
	v_mad_i64_i32 v[0:1], s[16:17], v0, s45, v[8:9]
	v_mov_b32_e32 v0, v120
	v_mov_b32_e32 v1, v121
	v_mov_b32_e32 v2, v122
	v_mov_b32_e32 v3, v123
	v_lshlrev_b32_e32 v58, 16, v0
	v_and_b32_e32 v59, 0xffff0000, v0
	v_lshlrev_b32_e32 v0, 16, v1
	v_and_b32_e32 v1, 0xffff0000, v1
	v_pk_add_f32 v[6:7], v[6:7], v[0:1] neg_lo:[0,1] neg_hi:[0,1]
	v_lshlrev_b32_e32 v0, 16, v2
	v_and_b32_e32 v1, 0xffff0000, v2
	v_pk_add_f32 v[52:53], v[52:53], v[0:1] neg_lo:[0,1] neg_hi:[0,1]
	v_lshlrev_b32_e32 v0, 16, v3
	v_and_b32_e32 v1, 0xffff0000, v3
	v_pk_add_f32 v[54:55], v[54:55], v[58:59] neg_lo:[0,1] neg_hi:[0,1]
	v_pk_add_f32 v[56:57], v[56:57], v[0:1] neg_lo:[0,1] neg_hi:[0,1]
.LBB0_362:
	s_or_b64 exec, exec, s[4:5]
	v_or_b32_e32 v58, 10, v4
	v_mad_i64_i32 v[0:1], s[4:5], v58, s45, v[8:9]
	v_mov_b32_e32 v0, v198
	v_mov_b32_e32 v1, v199
	v_mov_b32_e32 v2, v200
	v_mov_b32_e32 v3, v201
	v_or_b32_e32 v5, 11, v77
	v_ashrrev_i32_e32 v59, 31, v58
	v_lshlrev_b32_e32 v60, 16, v0
	v_and_b32_e32 v61, 0xffff0000, v0
	v_min_u32_e32 v0, v5, v67
	v_cvt_f32_ubyte0_e32 v0, v0
	v_lshlrev_b32_e32 v62, 16, v1
	v_and_b32_e32 v63, 0xffff0000, v1
	v_div_scale_f32 v1, s[4:5], v0, v0, 1.0
	v_lshlrev_b32_e32 v64, 16, v2
	v_and_b32_e32 v65, 0xffff0000, v2
	v_rcp_f32_e32 v2, v1
	v_lshlrev_b32_e32 v78, 16, v3
	v_and_b32_e32 v79, 0xffff0000, v3
	v_pk_add_f32 v[54:55], v[54:55], v[60:61]
	v_fma_f32 v3, -v1, v2, 1.0
	v_fmac_f32_e32 v2, v3, v2
	v_div_scale_f32 v3, vcc, 1.0, v0, 1.0
	v_mul_f32_e32 v80, v3, v2
	v_fma_f32 v81, -v1, v80, v3
	v_fmac_f32_e32 v80, v81, v2
	v_fma_f32 v1, -v1, v80, v3
	v_div_fmas_f32 v1, v1, v2, v80
	v_div_fixup_f32 v3, v1, v0, 1.0
	v_pk_add_f32 v[6:7], v[6:7], v[62:63]
	v_fma_f32 v0, v3, v54, -v60
	v_fma_f32 v1, v3, v55, -v61
	v_pk_add_f32 v[52:53], v[52:53], v[64:65]
	v_cvt_pk_bf16_f32 v0, v0, v1
	v_fma_f32 v1, v3, v6, -v62
	v_fma_f32 v2, v3, v7, -v63
	v_pk_add_f32 v[56:57], v[56:57], v[78:79]
	v_cvt_pk_bf16_f32 v1, v1, v2
	v_fma_f32 v2, v3, v52, -v64
	v_fma_f32 v60, v3, v53, -v65
	v_cvt_pk_bf16_f32 v2, v2, v60
	v_fma_f32 v60, v3, v56, -v78
	v_fma_f32 v3, v3, v57, -v79
	v_cvt_pk_bf16_f32 v3, v60, v3
	v_lshlrev_b64 v[60:61], 10, v[58:59]
	v_lshl_add_u64 v[60:61], v[10:11], 0, v[60:61]
	v_cmp_ge_u32_e32 vcc, v5, v67
	global_store_dwordx4 v[60:61], v[0:3], off
	s_and_saveexec_b64 s[4:5], vcc
	s_cbranch_execz .LBB0_364
	v_sub_u32_e32 v0, v58, v67
	v_or_b32_e32 v0, 1, v0
	v_mad_i64_i32 v[0:1], s[16:17], v0, s45, v[8:9]
	v_mov_b32_e32 v0, v124
	v_mov_b32_e32 v1, v125
	v_mov_b32_e32 v2, v126
	v_mov_b32_e32 v3, v127
	v_lshlrev_b32_e32 v58, 16, v0
	v_and_b32_e32 v59, 0xffff0000, v0
	v_lshlrev_b32_e32 v0, 16, v1
	v_and_b32_e32 v1, 0xffff0000, v1
	v_pk_add_f32 v[6:7], v[6:7], v[0:1] neg_lo:[0,1] neg_hi:[0,1]
	v_lshlrev_b32_e32 v0, 16, v2
	v_and_b32_e32 v1, 0xffff0000, v2
	v_pk_add_f32 v[52:53], v[52:53], v[0:1] neg_lo:[0,1] neg_hi:[0,1]
	v_lshlrev_b32_e32 v0, 16, v3
	v_and_b32_e32 v1, 0xffff0000, v3
	v_pk_add_f32 v[54:55], v[54:55], v[58:59] neg_lo:[0,1] neg_hi:[0,1]
	v_pk_add_f32 v[56:57], v[56:57], v[0:1] neg_lo:[0,1] neg_hi:[0,1]
; __device__ __forceinline__ unsigned cvt_pk_bf16(float lo, float hi) { unsigned r; asm volatile("v_cvt_pk_bf16_f32 %0, %1, %2" : "=v"(r) : "v"(lo), "v"(hi)); return r; }
; __device__ __forceinline__ void UNPACK8(const u32x4 q, float (&f)[8]) { f[0] = bflo(q.x); f[1] = bfhi(q.x); f[2] = bflo(q.y); f[3] = bfhi(q.y); f[4] = bflo(q.z); f[5] = bfhi(q.z); f[6] = bflo(q.w); f[7] = bfhi(q.w); }
; __device__ __forceinline__ void pool_chunk(PCP p, int chunk, int tid) {
;     ...
;         for (int i = 0; i < 16; ++i) { const int t = t0 + i, pos = pos0 + i;
;             const u32x4 zw = *(const u32x4*)(proj + (size_t)t * 1536 + c); float z[8]; UNPACK8(zw, z);
; #pragma unroll
;             for (int e = 0; e < 8; ++e) s[e] += z[e];
;             const int cnt = (pos + 1 < w) ? pos + 1 : w; const float inv = 1.0f / (float)cnt;
;             u32x4 o; o.x = cvt_pk_bf16(s[0] * inv - z[0], s[1] * inv - z[1]); o.y = cvt_pk_bf16(s[2] * inv - z[2], s[3] * inv - z[3]); o.z = cvt_pk_bf16(s[4] * inv - z[4], s[5] * inv - z[5]); o.w = cvt_pk_bf16(s[6] * inv - z[6], s[7] * inv - z[7]);
;             *(u32x4*)(pooled + (size_t)t * 512 + c) = o;
;             if (pos + 1 >= w) { const u32x4 ow = *(const u32x4*)(proj + (size_t)(t + 1 - w) * 1536 + c); float q[8]; UNPACK8(ow, q);
; #pragma unroll
;                 for (int e = 0; e < 8; ++e) s[e] -= q[e]; } }
.LBB0_364:
	s_or_b64 exec, exec, s[4:5]
	v_or_b32_e32 v58, 11, v4
	v_mad_i64_i32 v[0:1], s[4:5], v58, s45, v[8:9]
	v_mov_b32_e32 v0, v202
	v_mov_b32_e32 v1, v203
	v_mov_b32_e32 v2, v204
	v_mov_b32_e32 v3, v205
	v_or_b32_e32 v5, 12, v77
	v_ashrrev_i32_e32 v59, 31, v58
	v_lshlrev_b32_e32 v60, 16, v0
	v_and_b32_e32 v61, 0xffff0000, v0
	v_min_u32_e32 v0, v5, v67
	v_cvt_f32_ubyte0_e32 v0, v0
	v_lshlrev_b32_e32 v62, 16, v1
	v_and_b32_e32 v63, 0xffff0000, v1
	v_div_scale_f32 v1, s[4:5], v0, v0, 1.0
	v_lshlrev_b32_e32 v64, 16, v2
	v_and_b32_e32 v65, 0xffff0000, v2
	v_rcp_f32_e32 v2, v1
	v_lshlrev_b32_e32 v78, 16, v3
	v_and_b32_e32 v79, 0xffff0000, v3
	v_pk_add_f32 v[54:55], v[54:55], v[60:61]
	v_fma_f32 v3, -v1, v2, 1.0
	v_fmac_f32_e32 v2, v3, v2
	v_div_scale_f32 v3, vcc, 1.0, v0, 1.0
	v_mul_f32_e32 v80, v3, v2
	v_fma_f32 v81, -v1, v80, v3
	v_fmac_f32_e32 v80, v81, v2
	v_fma_f32 v1, -v1, v80, v3
	v_div_fmas_f32 v1, v1, v2, v80
	v_div_fixup_f32 v3, v1, v0, 1.0
	v_pk_add_f32 v[6:7], v[6:7], v[62:63]
	v_fma_f32 v0, v3, v54, -v60
	v_fma_f32 v1, v3, v55, -v61
	v_pk_add_f32 v[52:53], v[52:53], v[64:65]
	v_cvt_pk_bf16_f32 v0, v0, v1
	v_fma_f32 v1, v3, v6, -v62
	v_fma_f32 v2, v3, v7, -v63
	v_pk_add_f32 v[56:57], v[56:57], v[78:79]
	v_cvt_pk_bf16_f32 v1, v1, v2
	v_fma_f32 v2, v3, v52, -v64
	v_fma_f32 v60, v3, v53, -v65
	v_cvt_pk_bf16_f32 v2, v2, v60
	v_fma_f32 v60, v3, v56, -v78
	v_fma_f32 v3, v3, v57, -v79
	v_cvt_pk_bf16_f32 v3, v60, v3
	v_lshlrev_b64 v[60:61], 10, v[58:59]
	v_lshl_add_u64 v[60:61], v[10:11], 0, v[60:61]
	v_cmp_ge_u32_e32 vcc, v5, v67
	global_store_dwordx4 v[60:61], v[0:3], off
	s_and_saveexec_b64 s[4:5], vcc
	s_cbranch_execz .LBB0_366
	v_sub_u32_e32 v0, v58, v67
	v_add_u32_e32 v0, 1, v0
	v_mad_i64_i32 v[0:1], s[16:17], v0, s45, v[8:9]
	v_mov_b32_e32 v0, v128
	v_mov_b32_e32 v1, v129
	v_mov_b32_e32 v2, v130
	v_mov_b32_e32 v3, v131
	v_lshlrev_b32_e32 v58, 16, v0
	v_and_b32_e32 v59, 0xffff0000, v0
	v_lshlrev_b32_e32 v0, 16, v1
	v_and_b32_e32 v1, 0xffff0000, v1
	v_pk_add_f32 v[6:7], v[6:7], v[0:1] neg_lo:[0,1] neg_hi:[0,1]
	v_lshlrev_b32_e32 v0, 16, v2
	v_and_b32_e32 v1, 0xffff0000, v2
	v_pk_add_f32 v[52:53], v[52:53], v[0:1] neg_lo:[0,1] neg_hi:[0,1]
	v_lshlrev_b32_e32 v0, 16, v3
	v_and_b32_e32 v1, 0xffff0000, v3
	v_pk_add_f32 v[54:55], v[54:55], v[58:59] neg_lo:[0,1] neg_hi:[0,1]
	v_pk_add_f32 v[56:57], v[56:57], v[0:1] neg_lo:[0,1] neg_hi:[0,1]
.LBB0_366:
	s_or_b64 exec, exec, s[4:5]
	v_or_b32_e32 v58, 12, v4
	v_mad_i64_i32 v[0:1], s[4:5], v58, s45, v[8:9]
	v_mov_b32_e32 v0, v216
	v_mov_b32_e32 v1, v217
	v_mov_b32_e32 v2, v218
	v_mov_b32_e32 v3, v219
	v_or_b32_e32 v5, 13, v77
	v_ashrrev_i32_e32 v59, 31, v58
	v_lshlrev_b32_e32 v60, 16, v0
	v_and_b32_e32 v61, 0xffff0000, v0
	v_min_u32_e32 v0, v5, v67
	v_cvt_f32_ubyte0_e32 v0, v0
	v_lshlrev_b32_e32 v62, 16, v1
	v_and_b32_e32 v63, 0xffff0000, v1
	v_div_scale_f32 v1, s[4:5], v0, v0, 1.0
	v_lshlrev_b32_e32 v64, 16, v2
	v_and_b32_e32 v65, 0xffff0000, v2
	v_rcp_f32_e32 v2, v1
	v_lshlrev_b32_e32 v78, 16, v3
	v_and_b32_e32 v79, 0xffff0000, v3
	v_pk_add_f32 v[54:55], v[54:55], v[60:61]
	v_fma_f32 v3, -v1, v2, 1.0
	v_fmac_f32_e32 v2, v3, v2
	v_div_scale_f32 v3, vcc, 1.0, v0, 1.0
	v_mul_f32_e32 v80, v3, v2
	v_fma_f32 v81, -v1, v80, v3
	v_fmac_f32_e32 v80, v81, v2
	v_fma_f32 v1, -v1, v80, v3
	v_div_fmas_f32 v1, v1, v2, v80
	v_div_fixup_f32 v3, v1, v0, 1.0
	v_pk_add_f32 v[6:7], v[6:7], v[62:63]
	v_fma_f32 v0, v3, v54, -v60
	v_fma_f32 v1, v3, v55, -v61
	v_pk_add_f32 v[52:53], v[52:53], v[64:65]
	v_cvt_pk_bf16_f32 v0, v0, v1
	v_fma_f32 v1, v3, v6, -v62
	v_fma_f32 v2, v3, v7, -v63
	v_pk_add_f32 v[56:57], v[56:57], v[78:79]
	v_cvt_pk_bf16_f32 v1, v1, v2
	v_fma_f32 v2, v3, v52, -v64
	v_fma_f32 v60, v3, v53, -v65
	v_cvt_pk_bf16_f32 v2, v2, v60
	v_fma_f32 v60, v3, v56, -v78
	v_fma_f32 v3, v3, v57, -v79
	v_cvt_pk_bf16_f32 v3, v60, v3
	v_lshlrev_b64 v[60:61], 10, v[58:59]
	v_lshl_add_u64 v[60:61], v[10:11], 0, v[60:61]
	v_cmp_ge_u32_e32 vcc, v5, v67
	global_store_dwordx4 v[60:61], v[0:3], off
	s_and_saveexec_b64 s[4:5], vcc
	s_cbranch_execz .LBB0_368
	v_sub_u32_e32 v0, v58, v67
	v_or_b32_e32 v0, 1, v0
	v_mad_i64_i32 v[0:1], s[16:17], v0, s45, v[8:9]
	v_mov_b32_e32 v0, v132
	v_mov_b32_e32 v1, v133
	v_mov_b32_e32 v2, v134
	v_mov_b32_e32 v3, v135
	v_lshlrev_b32_e32 v58, 16, v0
	v_and_b32_e32 v59, 0xffff0000, v0
	v_lshlrev_b32_e32 v0, 16, v1
	v_and_b32_e32 v1, 0xffff0000, v1
	v_pk_add_f32 v[6:7], v[6:7], v[0:1] neg_lo:[0,1] neg_hi:[0,1]
	v_lshlrev_b32_e32 v0, 16, v2
	v_and_b32_e32 v1, 0xffff0000, v2
	v_pk_add_f32 v[52:53], v[52:53], v[0:1] neg_lo:[0,1] neg_hi:[0,1]
	v_lshlrev_b32_e32 v0, 16, v3
	v_and_b32_e32 v1, 0xffff0000, v3
	v_pk_add_f32 v[54:55], v[54:55], v[58:59] neg_lo:[0,1] neg_hi:[0,1]
	v_pk_add_f32 v[56:57], v[56:57], v[0:1] neg_lo:[0,1] neg_hi:[0,1]
; __device__ __forceinline__ unsigned cvt_pk_bf16(float lo, float hi) { unsigned r; asm volatile("v_cvt_pk_bf16_f32 %0, %1, %2" : "=v"(r) : "v"(lo), "v"(hi)); return r; }
; __device__ __forceinline__ void UNPACK8(const u32x4 q, float (&f)[8]) { f[0] = bflo(q.x); f[1] = bfhi(q.x); f[2] = bflo(q.y); f[3] = bfhi(q.y); f[4] = bflo(q.z); f[5] = bfhi(q.z); f[6] = bflo(q.w); f[7] = bfhi(q.w); }
; __device__ __forceinline__ void pool_chunk(PCP p, int chunk, int tid) {
;     ...
;         for (int i = 0; i < 16; ++i) { const int t = t0 + i, pos = pos0 + i;
;             const u32x4 zw = *(const u32x4*)(proj + (size_t)t * 1536 + c); float z[8]; UNPACK8(zw, z);
; #pragma unroll
;             for (int e = 0; e < 8; ++e) s[e] += z[e];
;             const int cnt = (pos + 1 < w) ? pos + 1 : w; const float inv = 1.0f / (float)cnt;
;             u32x4 o; o.x = cvt_pk_bf16(s[0] * inv - z[0], s[1] * inv - z[1]); o.y = cvt_pk_bf16(s[2] * inv - z[2], s[3] * inv - z[3]); o.z = cvt_pk_bf16(s[4] * inv - z[4], s[5] * inv - z[5]); o.w = cvt_pk_bf16(s[6] * inv - z[6], s[7] * inv - z[7]);
;             *(u32x4*)(pooled + (size_t)t * 512 + c) = o;
;             if (pos + 1 >= w) { const u32x4 ow = *(const u32x4*)(proj + (size_t)(t + 1 - w) * 1536 + c); float q[8]; UNPACK8(ow, q);
; #pragma unroll
;                 for (int e = 0; e < 8; ++e) s[e] -= q[e]; } }
.LBB0_368:
	s_or_b64 exec, exec, s[4:5]
	v_or_b32_e32 v58, 13, v4
	v_mad_i64_i32 v[0:1], s[4:5], v58, s45, v[8:9]
	v_mov_b32_e32 v0, v220
	v_mov_b32_e32 v1, v221
	v_mov_b32_e32 v2, v222
	v_mov_b32_e32 v3, v223
	v_or_b32_e32 v5, 14, v77
	v_ashrrev_i32_e32 v59, 31, v58
	v_lshlrev_b32_e32 v60, 16, v0
	v_and_b32_e32 v61, 0xffff0000, v0
	v_min_u32_e32 v0, v5, v67
	v_cvt_f32_ubyte0_e32 v0, v0
	v_lshlrev_b32_e32 v62, 16, v1
	v_and_b32_e32 v63, 0xffff0000, v1
	v_div_scale_f32 v1, s[4:5], v0, v0, 1.0
	v_lshlrev_b32_e32 v64, 16, v2
	v_and_b32_e32 v65, 0xffff0000, v2
	v_rcp_f32_e32 v2, v1
	v_lshlrev_b32_e32 v78, 16, v3
	v_and_b32_e32 v79, 0xffff0000, v3
	v_pk_add_f32 v[54:55], v[54:55], v[60:61]
	v_fma_f32 v3, -v1, v2, 1.0
	v_fmac_f32_e32 v2, v3, v2
	v_div_scale_f32 v3, vcc, 1.0, v0, 1.0
	v_mul_f32_e32 v80, v3, v2
	v_fma_f32 v81, -v1, v80, v3
	v_fmac_f32_e32 v80, v81, v2
	v_fma_f32 v1, -v1, v80, v3
	v_div_fmas_f32 v1, v1, v2, v80
	v_div_fixup_f32 v3, v1, v0, 1.0
	v_pk_add_f32 v[6:7], v[6:7], v[62:63]
	v_fma_f32 v0, v3, v54, -v60
	v_fma_f32 v1, v3, v55, -v61
	v_pk_add_f32 v[52:53], v[52:53], v[64:65]
	v_cvt_pk_bf16_f32 v0, v0, v1
	v_fma_f32 v1, v3, v6, -v62
	v_fma_f32 v2, v3, v7, -v63
	v_pk_add_f32 v[56:57], v[56:57], v[78:79]
	v_cvt_pk_bf16_f32 v1, v1, v2
	v_fma_f32 v2, v3, v52, -v64
	v_fma_f32 v60, v3, v53, -v65
	v_cvt_pk_bf16_f32 v2, v2, v60
	v_fma_f32 v60, v3, v56, -v78
	v_fma_f32 v3, v3, v57, -v79
	v_cvt_pk_bf16_f32 v3, v60, v3
	v_lshlrev_b64 v[60:61], 10, v[58:59]
	v_lshl_add_u64 v[60:61], v[10:11], 0, v[60:61]
	v_cmp_ge_u32_e32 vcc, v5, v67
	global_store_dwordx4 v[60:61], v[0:3], off
	s_and_saveexec_b64 s[4:5], vcc
	s_cbranch_execz .LBB0_370
	v_sub_u32_e32 v0, v58, v67
	v_add_u32_e32 v0, 1, v0
	v_mad_i64_i32 v[0:1], s[16:17], v0, s45, v[8:9]
	v_mov_b32_e32 v0, v136
	v_mov_b32_e32 v1, v137
	v_mov_b32_e32 v2, v138
	v_mov_b32_e32 v3, v139
	v_lshlrev_b32_e32 v58, 16, v0
	v_and_b32_e32 v59, 0xffff0000, v0
	v_lshlrev_b32_e32 v0, 16, v1
	v_and_b32_e32 v1, 0xffff0000, v1
	v_pk_add_f32 v[6:7], v[6:7], v[0:1] neg_lo:[0,1] neg_hi:[0,1]
	v_lshlrev_b32_e32 v0, 16, v2
	v_and_b32_e32 v1, 0xffff0000, v2
	v_pk_add_f32 v[52:53], v[52:53], v[0:1] neg_lo:[0,1] neg_hi:[0,1]
	v_lshlrev_b32_e32 v0, 16, v3
	v_and_b32_e32 v1, 0xffff0000, v3
	v_pk_add_f32 v[54:55], v[54:55], v[58:59] neg_lo:[0,1] neg_hi:[0,1]
	v_pk_add_f32 v[56:57], v[56:57], v[0:1] neg_lo:[0,1] neg_hi:[0,1]
.LBB0_370:
	s_or_b64 exec, exec, s[4:5]
	v_or_b32_e32 v58, 14, v4
	v_mad_i64_i32 v[0:1], s[4:5], v58, s45, v[8:9]
	v_mov_b32_e32 v0, v226
	v_mov_b32_e32 v1, v227
	v_mov_b32_e32 v2, v228
	v_mov_b32_e32 v3, v229
	v_or_b32_e32 v77, 15, v77
	v_ashrrev_i32_e32 v59, 31, v58
	v_lshlrev_b32_e32 v60, 16, v0
	v_and_b32_e32 v61, 0xffff0000, v0
	v_min_u32_e32 v0, v77, v67
	v_cvt_f32_ubyte0_e32 v0, v0
	v_lshlrev_b32_e32 v62, 16, v1
	v_and_b32_e32 v63, 0xffff0000, v1
	v_div_scale_f32 v1, s[4:5], v0, v0, 1.0
	v_lshlrev_b32_e32 v64, 16, v2
	v_and_b32_e32 v65, 0xffff0000, v2
	v_rcp_f32_e32 v2, v1
	v_lshlrev_b32_e32 v78, 16, v3
	v_and_b32_e32 v79, 0xffff0000, v3
	v_pk_add_f32 v[4:5], v[54:55], v[60:61]
	v_fma_f32 v3, -v1, v2, 1.0
	v_fmac_f32_e32 v2, v3, v2
	v_div_scale_f32 v3, vcc, 1.0, v0, 1.0
	v_pk_add_f32 v[54:55], v[56:57], v[78:79]
	v_mul_f32_e32 v56, v3, v2
	v_fma_f32 v57, -v1, v56, v3
	v_fmac_f32_e32 v56, v57, v2
	v_fma_f32 v1, -v1, v56, v3
	v_div_fmas_f32 v1, v1, v2, v56
	v_div_fixup_f32 v3, v1, v0, 1.0
	v_pk_add_f32 v[6:7], v[6:7], v[62:63]
	v_fma_f32 v0, v3, v4, -v60
	v_fma_f32 v1, v3, v5, -v61
	v_pk_add_f32 v[52:53], v[52:53], v[64:65]
	v_cvt_pk_bf16_f32 v0, v0, v1
	v_fma_f32 v1, v3, v6, -v62
	v_fma_f32 v2, v3, v7, -v63
	v_cvt_pk_bf16_f32 v1, v1, v2
	v_fma_f32 v2, v3, v52, -v64
	v_fma_f32 v56, v3, v53, -v65
	v_cvt_pk_bf16_f32 v2, v2, v56
	v_fma_f32 v56, v3, v54, -v78
	v_fma_f32 v3, v3, v55, -v79
	v_cvt_pk_bf16_f32 v3, v56, v3
	v_lshlrev_b64 v[56:57], 10, v[58:59]
	v_lshl_add_u64 v[56:57], v[10:11], 0, v[56:57]
	v_cmp_ge_u32_e32 vcc, v77, v67
	global_store_dwordx4 v[56:57], v[0:3], off
	s_and_saveexec_b64 s[4:5], vcc
	s_cbranch_execz .LBB0_372
	v_sub_u32_e32 v0, v58, v67
	v_or_b32_e32 v0, 1, v0
	v_mad_i64_i32 v[0:1], s[16:17], v0, s45, v[8:9]
	v_mov_b32_e32 v0, v140
	v_mov_b32_e32 v1, v141
	v_mov_b32_e32 v2, v142
	v_mov_b32_e32 v3, v143
	v_lshlrev_b32_e32 v56, 16, v0
	v_and_b32_e32 v57, 0xffff0000, v0
	v_lshlrev_b32_e32 v0, 16, v1
	v_and_b32_e32 v1, 0xffff0000, v1
	v_pk_add_f32 v[6:7], v[6:7], v[0:1] neg_lo:[0,1] neg_hi:[0,1]
	v_lshlrev_b32_e32 v0, 16, v2
	v_and_b32_e32 v1, 0xffff0000, v2
	v_pk_add_f32 v[52:53], v[52:53], v[0:1] neg_lo:[0,1] neg_hi:[0,1]
	v_lshlrev_b32_e32 v0, 16, v3
	v_and_b32_e32 v1, 0xffff0000, v3
	v_pk_add_f32 v[4:5], v[4:5], v[56:57] neg_lo:[0,1] neg_hi:[0,1]
	v_pk_add_f32 v[54:55], v[54:55], v[0:1] neg_lo:[0,1] neg_hi:[0,1]
; __device__ __forceinline__ unsigned cvt_pk_bf16(float lo, float hi) { unsigned r; asm volatile("v_cvt_pk_bf16_f32 %0, %1, %2" : "=v"(r) : "v"(lo), "v"(hi)); return r; }
; __device__ __forceinline__ void UNPACK8(const u32x4 q, float (&f)[8]) { f[0] = bflo(q.x); f[1] = bfhi(q.x); f[2] = bflo(q.y); f[3] = bfhi(q.y); f[4] = bflo(q.z); f[5] = bfhi(q.z); f[6] = bflo(q.w); f[7] = bfhi(q.w); }
; __device__ __forceinline__ void pool_chunk(PCP p, int chunk, int tid) {
;     ...
;         for (int i = 0; i < 16; ++i) { const int t = t0 + i, pos = pos0 + i;
;             const u32x4 zw = *(const u32x4*)(proj + (size_t)t * 1536 + c); float z[8]; UNPACK8(zw, z);
; #pragma unroll
;             for (int e = 0; e < 8; ++e) s[e] += z[e];
;             const int cnt = (pos + 1 < w) ? pos + 1 : w; const float inv = 1.0f / (float)cnt;
;             u32x4 o; o.x = cvt_pk_bf16(s[0] * inv - z[0], s[1] * inv - z[1]); o.y = cvt_pk_bf16(s[2] * inv - z[2], s[3] * inv - z[3]); o.z = cvt_pk_bf16(s[4] * inv - z[4], s[5] * inv - z[5]); o.w = cvt_pk_bf16(s[6] * inv - z[6], s[7] * inv - z[7]);
;             *(u32x4*)(pooled + (size_t)t * 512 + c) = o;
;             if (pos + 1 >= w) { const u32x4 ow = *(const u32x4*)(proj + (size_t)(t + 1 - w) * 1536 + c); float q[8]; UNPACK8(ow, q);
; #pragma unroll
;                 for (int e = 0; e < 8; ++e) s[e] -= q[e]; } }
; __device__ __forceinline__ void sguprep_chunk(PCP p, int j, LAS unsigned char* lds, int it, int tid) {
;     ...
;         for (int s0 = 0; s0 < 16; ++s0) { const int s = wid * 16 + s0; const u32x4 vw = *(const u32x4*)(proj + (T0 + s) * 1536 + 1024 + lane * 8); float v[8]; UNPACK8(vw, v); float ss = 0.f;
; #pragma unroll
;             for (int e = 0; e < 8; ++e) ss += v[e] * v[e];
;             ss = wave_sum(ss); if (lane == 0) rstd[s] = rsqrtf(ss * (1.0f / 512.0f) + EPS); }
.LBB0_372:
	s_or_b64 exec, exec, s[4:5]
	v_or_b32_e32 v56, 15, v76
	v_mad_i64_i32 v[0:1], s[4:5], v56, s45, v[8:9]
	v_mov_b32_e32 v0, v230
	v_mov_b32_e32 v1, v231
	v_mov_b32_e32 v2, v232
	v_mov_b32_e32 v3, v233
	v_ashrrev_i32_e32 v57, 31, v56
	s_ashr_i32 s3, s2, 31
	s_lshl_b64 s[4:5], s[2:3], 7
	v_lshlrev_b32_e32 v58, 16, v0
	v_and_b32_e32 v0, 0xffff0000, v0
	v_lshlrev_b32_e32 v59, 16, v1
	v_and_b32_e32 v1, 0xffff0000, v1
	v_add_f32_e32 v4, v4, v58
	v_add_f32_e32 v5, v5, v0
	v_lshlrev_b32_e32 v60, 16, v2
	v_and_b32_e32 v2, 0xffff0000, v2
	v_add_f32_e32 v6, v6, v59
	v_add_f32_e32 v7, v7, v1
	v_fma_f32 v4, v68, v4, -v58
	v_fma_f32 v0, v68, v5, -v0
	v_lshlrev_b32_e32 v61, 16, v3
	v_and_b32_e32 v3, 0xffff0000, v3
	v_add_f32_e32 v52, v52, v60
	v_add_f32_e32 v53, v53, v2
	v_cvt_pk_bf16_f32 v0, v4, v0
	v_fma_f32 v4, v68, v6, -v59
	v_fma_f32 v1, v68, v7, -v1
	v_add_f32_e32 v54, v54, v61
	v_add_f32_e32 v55, v55, v3
	v_cvt_pk_bf16_f32 v1, v4, v1
	v_fma_f32 v4, v68, v52, -v60
	v_fma_f32 v2, v68, v53, -v2
	v_cvt_pk_bf16_f32 v2, v4, v2
	v_fma_f32 v4, v68, v54, -v61
	v_fma_f32 v3, v68, v55, -v3
	v_cvt_pk_bf16_f32 v3, v4, v3
	v_lshlrev_b64 v[4:5], 10, v[56:57]
	v_lshl_add_u64 v[4:5], v[10:11], 0, v[4:5]
	global_store_dwordx4 v[4:5], v[0:3], off
	v_xor_b32_e32 v4, 2, v207
	v_xor_b32_e32 v6, 1, v207
	v_and_b32_e32 v0, 64, v207
	v_add_u32_e32 v5, 64, v0
	v_xor_b32_e32 v0, 32, v207
	v_cmp_lt_i32_e32 vcc, v0, v5
	v_xor_b32_e32 v1, 16, v207
	v_xor_b32_e32 v2, 8, v207
	v_cndmask_b32_e32 v0, v207, v0, vcc
	v_cmp_lt_i32_e32 vcc, v1, v5
	v_xor_b32_e32 v3, 4, v207
	v_lshlrev_b32_e32 v0, 2, v0
	v_cndmask_b32_e32 v1, v207, v1, vcc
	v_cmp_lt_i32_e32 vcc, v2, v5
	v_lshlrev_b32_e32 v1, 2, v1
	s_nop 0
	v_cndmask_b32_e32 v2, v207, v2, vcc
	v_cmp_lt_i32_e32 vcc, v3, v5
	v_lshlrev_b32_e32 v2, 2, v2
	s_nop 0
	v_cndmask_b32_e32 v3, v207, v3, vcc
	v_cmp_lt_i32_e32 vcc, v4, v5
	v_lshlrev_b32_e32 v3, 2, v3
	s_nop 0
	v_cndmask_b32_e32 v4, v207, v4, vcc
	v_cmp_lt_i32_e32 vcc, v6, v5
	v_lshlrev_b32_e32 v4, 2, v4
	s_nop 0
	v_cndmask_b32_e32 v5, v207, v6, vcc
	v_lshl_add_u64 v[84:85], s[4:5], 0, v[12:13]
	v_mad_u64_u32 v[86:87], s[16:17], v84, s45, v[44:45]
	v_mad_i32_i24 v87, v85, s45, v87
	global_load_dwordx4 v[84:87], v[86:87], off offset:2048
	v_lshl_add_u64 v[88:89], s[4:5], 0, v[14:15]
	v_mad_u64_u32 v[90:91], s[16:17], v88, s45, v[44:45]
	v_mad_i32_i24 v91, v89, s45, v91
	global_load_dwordx4 v[88:91], v[90:91], off offset:2048
	v_lshl_add_u64 v[92:93], s[4:5], 0, v[16:17]
	v_mad_u64_u32 v[94:95], s[16:17], v92, s45, v[44:45]
	v_mad_i32_i24 v95, v93, s45, v95
	global_load_dwordx4 v[92:95], v[94:95], off offset:2048
	v_lshl_add_u64 v[96:97], s[4:5], 0, v[18:19]
	v_mad_u64_u32 v[98:99], s[16:17], v96, s45, v[44:45]
	v_mad_i32_i24 v99, v97, s45, v99
	global_load_dwordx4 v[96:99], v[98:99], off offset:2048
	v_lshl_add_u64 v[100:101], s[4:5], 0, v[20:21]
	v_mad_u64_u32 v[102:103], s[16:17], v100, s45, v[44:45]
	v_mad_i32_i24 v103, v101, s45, v103
	global_load_dwordx4 v[100:103], v[102:103], off offset:2048
	v_lshl_add_u64 v[104:105], s[4:5], 0, v[22:23]
	v_mad_u64_u32 v[106:107], s[16:17], v104, s45, v[44:45]
	v_mad_i32_i24 v107, v105, s45, v107
	global_load_dwordx4 v[104:107], v[106:107], off offset:2048
	v_lshl_add_u64 v[108:109], s[4:5], 0, v[24:25]
	v_mad_u64_u32 v[110:111], s[16:17], v108, s45, v[44:45]
	v_mad_i32_i24 v111, v109, s45, v111
	global_load_dwordx4 v[108:111], v[110:111], off offset:2048
	v_lshl_add_u64 v[112:113], s[4:5], 0, v[26:27]
	v_mad_u64_u32 v[114:115], s[16:17], v112, s45, v[44:45]
	v_mad_i32_i24 v115, v113, s45, v115
	global_load_dwordx4 v[112:115], v[114:115], off offset:2048
	v_lshl_add_u64 v[116:117], s[4:5], 0, v[28:29]
	v_mad_u64_u32 v[118:119], s[16:17], v116, s45, v[44:45]
	v_mad_i32_i24 v119, v117, s45, v119
	global_load_dwordx4 v[116:119], v[118:119], off offset:2048
	v_lshl_add_u64 v[120:121], s[4:5], 0, v[30:31]
	v_mad_u64_u32 v[122:123], s[16:17], v120, s45, v[44:45]
	v_mad_i32_i24 v123, v121, s45, v123
	global_load_dwordx4 v[120:123], v[122:123], off offset:2048
	v_lshl_add_u64 v[124:125], s[4:5], 0, v[32:33]
	v_mad_u64_u32 v[126:127], s[16:17], v124, s45, v[44:45]
	v_mad_i32_i24 v127, v125, s45, v127
	global_load_dwordx4 v[124:127], v[126:127], off offset:2048
	v_lshl_add_u64 v[128:129], s[4:5], 0, v[34:35]
	v_mad_u64_u32 v[130:131], s[16:17], v128, s45, v[44:45]
	v_mad_i32_i24 v131, v129, s45, v131
	global_load_dwordx4 v[128:131], v[130:131], off offset:2048
	v_lshl_add_u64 v[132:133], s[4:5], 0, v[36:37]
	v_mad_u64_u32 v[134:135], s[16:17], v132, s45, v[44:45]
	v_mad_i32_i24 v135, v133, s45, v135
	global_load_dwordx4 v[132:135], v[134:135], off offset:2048
	v_lshl_add_u64 v[136:137], s[4:5], 0, v[38:39]
	v_mad_u64_u32 v[138:139], s[16:17], v136, s45, v[44:45]
	v_mad_i32_i24 v139, v137, s45, v139
	global_load_dwordx4 v[136:139], v[138:139], off offset:2048
	v_lshl_add_u64 v[140:141], s[4:5], 0, v[40:41]
	v_mad_u64_u32 v[142:143], s[16:17], v140, s45, v[44:45]
	v_mad_i32_i24 v143, v141, s45, v143
	global_load_dwordx4 v[140:143], v[142:143], off offset:2048
	v_lshl_add_u64 v[144:145], s[4:5], 0, v[42:43]
	v_mad_u64_u32 v[146:147], s[16:17], v144, s45, v[44:45]
	v_mad_i32_i24 v147, v145, s45, v147
	global_load_dwordx4 v[144:147], v[146:147], off offset:2048
	s_waitcnt vmcnt(0)
	v_lshl_add_u64 v[6:7], s[4:5], 0, v[12:13]
	v_mad_u64_u32 v[52:53], s[16:17], v6, s45, v[44:45]
	v_mad_i32_i24 v53, v7, s45, v53
	v_mov_b32_e32 v52, v84
	v_mov_b32_e32 v53, v85
	v_mov_b32_e32 v54, v86
	v_mov_b32_e32 v55, v87
	v_lshlrev_b32_e32 v5, 2, v5
	v_and_b32_e32 v7, 0xffff0000, v52
	v_lshlrev_b32_e32 v6, 16, v52
	v_mul_f32_e32 v7, v7, v7
	v_lshlrev_b32_e32 v52, 16, v53
	v_fmac_f32_e32 v7, v6, v6
	v_and_b32_e32 v53, 0xffff0000, v53
	v_fmac_f32_e32 v7, v52, v52
	v_lshlrev_b32_e32 v56, 16, v54
	v_fmac_f32_e32 v7, v53, v53
	v_and_b32_e32 v54, 0xffff0000, v54
	v_fmac_f32_e32 v7, v56, v56
	v_lshlrev_b32_e32 v57, 16, v55
	v_fmac_f32_e32 v7, v54, v54
	v_and_b32_e32 v55, 0xffff0000, v55
	v_fmac_f32_e32 v7, v57, v57
	v_fmac_f32_e32 v7, v55, v55
	ds_bpermute_b32 v6, v0, v7
	s_waitcnt lgkmcnt(0)
	v_add_f32_e32 v6, v7, v6
	ds_bpermute_b32 v7, v1, v6
	s_waitcnt lgkmcnt(0)
	v_add_f32_e32 v6, v6, v7
	ds_bpermute_b32 v7, v2, v6
	s_waitcnt lgkmcnt(0)
	v_add_f32_e32 v6, v6, v7
	ds_bpermute_b32 v7, v3, v6
	s_waitcnt lgkmcnt(0)
	v_add_f32_e32 v6, v6, v7
	ds_bpermute_b32 v7, v4, v6
	s_waitcnt lgkmcnt(0)
	v_add_f32_e32 v6, v6, v7
	ds_bpermute_b32 v7, v5, v6
	s_and_saveexec_b64 s[16:17], s[14:15]
	s_cbranch_execz .LBB0_374
	s_waitcnt lgkmcnt(0)
	v_add_f32_e32 v6, v6, v7
	v_fmamk_f32 v6, v6, 0x3b000000, v208
	v_mul_f32_e32 v7, 0x4b800000, v6
	v_cmp_gt_f32_e32 vcc, s44, v6
	s_nop 1
	v_cndmask_b32_e32 v6, v6, v7, vcc
	v_rsq_f32_e32 v6, v6
	s_nop 0
	v_mul_f32_e32 v7, 0x45800000, v6
	v_cndmask_b32_e32 v6, v6, v7, vcc
	ds_write_b32 v69, v6
; __device__ __forceinline__ void UNPACK8(const u32x4 q, float (&f)[8]) { f[0] = bflo(q.x); f[1] = bfhi(q.x); f[2] = bflo(q.y); f[3] = bfhi(q.y); f[4] = bflo(q.z); f[5] = bfhi(q.z); f[6] = bflo(q.w); f[7] = bfhi(q.w); }
; __device__ __forceinline__ void sguprep_chunk(PCP p, int j, LAS unsigned char* lds, int it, int tid) {
;     ...
;         for (int s0 = 0; s0 < 16; ++s0) { const int s = wid * 16 + s0; const u32x4 vw = *(const u32x4*)(proj + (T0 + s) * 1536 + 1024 + lane * 8); float v[8]; UNPACK8(vw, v); float ss = 0.f;
; #pragma unroll
;             for (int e = 0; e < 8; ++e) ss += v[e] * v[e];
;             ss = wave_sum(ss); if (lane == 0) rstd[s] = rsqrtf(ss * (1.0f / 512.0f) + EPS); }
.LBB0_374:
	s_or_b64 exec, exec, s[16:17]
	s_waitcnt lgkmcnt(0)
	v_lshl_add_u64 v[6:7], s[4:5], 0, v[14:15]
	v_mad_u64_u32 v[52:53], s[16:17], v6, s45, v[44:45]
	v_mad_i32_i24 v53, v7, s45, v53
	v_mov_b32_e32 v52, v88
	v_mov_b32_e32 v53, v89
	v_mov_b32_e32 v54, v90
	v_mov_b32_e32 v55, v91
	v_and_b32_e32 v7, 0xffff0000, v52
	v_lshlrev_b32_e32 v6, 16, v52
	v_mul_f32_e32 v7, v7, v7
	v_lshlrev_b32_e32 v52, 16, v53
	v_fmac_f32_e32 v7, v6, v6
	v_and_b32_e32 v53, 0xffff0000, v53
	v_fmac_f32_e32 v7, v52, v52
	v_lshlrev_b32_e32 v56, 16, v54
	v_fmac_f32_e32 v7, v53, v53
	v_and_b32_e32 v54, 0xffff0000, v54
	v_fmac_f32_e32 v7, v56, v56
	v_lshlrev_b32_e32 v57, 16, v55
	v_fmac_f32_e32 v7, v54, v54
	v_and_b32_e32 v55, 0xffff0000, v55
	v_fmac_f32_e32 v7, v57, v57
	v_fmac_f32_e32 v7, v55, v55
	ds_bpermute_b32 v6, v0, v7
	s_waitcnt lgkmcnt(0)
	v_add_f32_e32 v6, v7, v6
	ds_bpermute_b32 v7, v1, v6
	s_waitcnt lgkmcnt(0)
	v_add_f32_e32 v6, v6, v7
	ds_bpermute_b32 v7, v2, v6
	s_waitcnt lgkmcnt(0)
	v_add_f32_e32 v6, v6, v7
	ds_bpermute_b32 v7, v3, v6
	s_waitcnt lgkmcnt(0)
	v_add_f32_e32 v6, v6, v7
	ds_bpermute_b32 v7, v4, v6
	s_waitcnt lgkmcnt(0)
	v_add_f32_e32 v6, v6, v7
	ds_bpermute_b32 v7, v5, v6
	s_and_saveexec_b64 s[16:17], s[14:15]
	s_cbranch_execz .LBB0_376
	s_waitcnt lgkmcnt(0)
	v_add_f32_e32 v6, v6, v7
	v_fmamk_f32 v6, v6, 0x3b000000, v208
	v_mul_f32_e32 v7, 0x4b800000, v6
	v_cmp_gt_f32_e32 vcc, s44, v6
	s_nop 1
	v_cndmask_b32_e32 v6, v6, v7, vcc
	v_rsq_f32_e32 v6, v6
	s_nop 0
	v_mul_f32_e32 v7, 0x45800000, v6
	v_cndmask_b32_e32 v6, v6, v7, vcc
	ds_write_b32 v69, v6 offset:4
.LBB0_376:
	s_or_b64 exec, exec, s[16:17]
	s_waitcnt lgkmcnt(0)
	v_lshl_add_u64 v[6:7], s[4:5], 0, v[16:17]
	v_mad_u64_u32 v[52:53], s[16:17], v6, s45, v[44:45]
	v_mad_i32_i24 v53, v7, s45, v53
	v_mov_b32_e32 v52, v92
	v_mov_b32_e32 v53, v93
	v_mov_b32_e32 v54, v94
	v_mov_b32_e32 v55, v95
	v_and_b32_e32 v7, 0xffff0000, v52
	v_lshlrev_b32_e32 v6, 16, v52
	v_mul_f32_e32 v7, v7, v7
	v_lshlrev_b32_e32 v52, 16, v53
	v_fmac_f32_e32 v7, v6, v6
	v_and_b32_e32 v53, 0xffff0000, v53
	v_fmac_f32_e32 v7, v52, v52
	v_lshlrev_b32_e32 v56, 16, v54
	v_fmac_f32_e32 v7, v53, v53
	v_and_b32_e32 v54, 0xffff0000, v54
	v_fmac_f32_e32 v7, v56, v56
	v_lshlrev_b32_e32 v57, 16, v55
	v_fmac_f32_e32 v7, v54, v54
	v_and_b32_e32 v55, 0xffff0000, v55
	v_fmac_f32_e32 v7, v57, v57
	v_fmac_f32_e32 v7, v55, v55
	ds_bpermute_b32 v6, v0, v7
	s_waitcnt lgkmcnt(0)
	v_add_f32_e32 v6, v7, v6
	ds_bpermute_b32 v7, v1, v6
	s_waitcnt lgkmcnt(0)
	v_add_f32_e32 v6, v6, v7
	ds_bpermute_b32 v7, v2, v6
	s_waitcnt lgkmcnt(0)
	v_add_f32_e32 v6, v6, v7
	ds_bpermute_b32 v7, v3, v6
	s_waitcnt lgkmcnt(0)
	v_add_f32_e32 v6, v6, v7
	ds_bpermute_b32 v7, v4, v6
	s_waitcnt lgkmcnt(0)
	v_add_f32_e32 v6, v6, v7
	ds_bpermute_b32 v7, v5, v6
	s_and_saveexec_b64 s[16:17], s[14:15]
	s_cbranch_execz .LBB0_378
	s_waitcnt lgkmcnt(0)
	v_add_f32_e32 v6, v6, v7
	v_fmamk_f32 v6, v6, 0x3b000000, v208
	v_mul_f32_e32 v7, 0x4b800000, v6
	v_cmp_gt_f32_e32 vcc, s44, v6
	s_nop 1
	v_cndmask_b32_e32 v6, v6, v7, vcc
	v_rsq_f32_e32 v6, v6
	s_nop 0
	v_mul_f32_e32 v7, 0x45800000, v6
	v_cndmask_b32_e32 v6, v6, v7, vcc
	ds_write_b32 v69, v6 offset:8
.LBB0_378:
	s_or_b64 exec, exec, s[16:17]
	s_waitcnt lgkmcnt(0)
	v_lshl_add_u64 v[6:7], s[4:5], 0, v[18:19]
	v_mad_u64_u32 v[52:53], s[16:17], v6, s45, v[44:45]
	v_mad_i32_i24 v53, v7, s45, v53
	v_mov_b32_e32 v52, v96
	v_mov_b32_e32 v53, v97
	v_mov_b32_e32 v54, v98
	v_mov_b32_e32 v55, v99
	v_and_b32_e32 v7, 0xffff0000, v52
	v_lshlrev_b32_e32 v6, 16, v52
	v_mul_f32_e32 v7, v7, v7
	v_lshlrev_b32_e32 v52, 16, v53
	v_fmac_f32_e32 v7, v6, v6
	v_and_b32_e32 v53, 0xffff0000, v53
	v_fmac_f32_e32 v7, v52, v52
	v_lshlrev_b32_e32 v56, 16, v54
	v_fmac_f32_e32 v7, v53, v53
	v_and_b32_e32 v54, 0xffff0000, v54
	v_fmac_f32_e32 v7, v56, v56
	v_lshlrev_b32_e32 v57, 16, v55
	v_fmac_f32_e32 v7, v54, v54
	v_and_b32_e32 v55, 0xffff0000, v55
	v_fmac_f32_e32 v7, v57, v57
	v_fmac_f32_e32 v7, v55, v55
	ds_bpermute_b32 v6, v0, v7
	s_waitcnt lgkmcnt(0)
	v_add_f32_e32 v6, v7, v6
	ds_bpermute_b32 v7, v1, v6
	s_waitcnt lgkmcnt(0)
	v_add_f32_e32 v6, v6, v7
	ds_bpermute_b32 v7, v2, v6
	s_waitcnt lgkmcnt(0)
	v_add_f32_e32 v6, v6, v7
	ds_bpermute_b32 v7, v3, v6
	s_waitcnt lgkmcnt(0)
	v_add_f32_e32 v6, v6, v7
	ds_bpermute_b32 v7, v4, v6
	s_waitcnt lgkmcnt(0)
	v_add_f32_e32 v6, v6, v7
	ds_bpermute_b32 v7, v5, v6
	s_and_saveexec_b64 s[16:17], s[14:15]
	s_cbranch_execz .LBB0_380
	s_waitcnt lgkmcnt(0)
	v_add_f32_e32 v6, v6, v7
	v_fmamk_f32 v6, v6, 0x3b000000, v208
	v_mul_f32_e32 v7, 0x4b800000, v6
	v_cmp_gt_f32_e32 vcc, s44, v6
	s_nop 1
	v_cndmask_b32_e32 v6, v6, v7, vcc
	v_rsq_f32_e32 v6, v6
	s_nop 0
	v_mul_f32_e32 v7, 0x45800000, v6
	v_cndmask_b32_e32 v6, v6, v7, vcc
	ds_write_b32 v69, v6 offset:12
.LBB0_380:
	s_or_b64 exec, exec, s[16:17]
	s_waitcnt lgkmcnt(0)
	v_lshl_add_u64 v[6:7], s[4:5], 0, v[20:21]
	v_mad_u64_u32 v[52:53], s[16:17], v6, s45, v[44:45]
	v_mad_i32_i24 v53, v7, s45, v53
	v_mov_b32_e32 v52, v100
	v_mov_b32_e32 v53, v101
	v_mov_b32_e32 v54, v102
	v_mov_b32_e32 v55, v103
	v_and_b32_e32 v7, 0xffff0000, v52
	v_lshlrev_b32_e32 v6, 16, v52
	v_mul_f32_e32 v7, v7, v7
	v_lshlrev_b32_e32 v52, 16, v53
	v_fmac_f32_e32 v7, v6, v6
	v_and_b32_e32 v53, 0xffff0000, v53
	v_fmac_f32_e32 v7, v52, v52
	v_lshlrev_b32_e32 v56, 16, v54
	v_fmac_f32_e32 v7, v53, v53
	v_and_b32_e32 v54, 0xffff0000, v54
	v_fmac_f32_e32 v7, v56, v56
	v_lshlrev_b32_e32 v57, 16, v55
	v_fmac_f32_e32 v7, v54, v54
	v_and_b32_e32 v55, 0xffff0000, v55
	v_fmac_f32_e32 v7, v57, v57
	v_fmac_f32_e32 v7, v55, v55
	ds_bpermute_b32 v6, v0, v7
	s_waitcnt lgkmcnt(0)
	v_add_f32_e32 v6, v7, v6
	ds_bpermute_b32 v7, v1, v6
	s_waitcnt lgkmcnt(0)
	v_add_f32_e32 v6, v6, v7
	ds_bpermute_b32 v7, v2, v6
	s_waitcnt lgkmcnt(0)
	v_add_f32_e32 v6, v6, v7
	ds_bpermute_b32 v7, v3, v6
	s_waitcnt lgkmcnt(0)
	v_add_f32_e32 v6, v6, v7
	ds_bpermute_b32 v7, v4, v6
	s_waitcnt lgkmcnt(0)
	v_add_f32_e32 v6, v6, v7
	ds_bpermute_b32 v7, v5, v6
	s_and_saveexec_b64 s[16:17], s[14:15]
	s_cbranch_execz .LBB0_382
	s_waitcnt lgkmcnt(0)
	v_add_f32_e32 v6, v6, v7
	v_fmamk_f32 v6, v6, 0x3b000000, v208
	v_mul_f32_e32 v7, 0x4b800000, v6
	v_cmp_gt_f32_e32 vcc, s44, v6
	s_nop 1
	v_cndmask_b32_e32 v6, v6, v7, vcc
	v_rsq_f32_e32 v6, v6
	s_nop 0
	v_mul_f32_e32 v7, 0x45800000, v6
	v_cndmask_b32_e32 v6, v6, v7, vcc
	ds_write_b32 v69, v6 offset:16
; __device__ __forceinline__ void UNPACK8(const u32x4 q, float (&f)[8]) { f[0] = bflo(q.x); f[1] = bfhi(q.x); f[2] = bflo(q.y); f[3] = bfhi(q.y); f[4] = bflo(q.z); f[5] = bfhi(q.z); f[6] = bflo(q.w); f[7] = bfhi(q.w); }
; __device__ __forceinline__ void sguprep_chunk(PCP p, int j, LAS unsigned char* lds, int it, int tid) {
;     ...
;         for (int s0 = 0; s0 < 16; ++s0) { const int s = wid * 16 + s0; const u32x4 vw = *(const u32x4*)(proj + (T0 + s) * 1536 + 1024 + lane * 8); float v[8]; UNPACK8(vw, v); float ss = 0.f;
; #pragma unroll
;             for (int e = 0; e < 8; ++e) ss += v[e] * v[e];
;             ss = wave_sum(ss); if (lane == 0) rstd[s] = rsqrtf(ss * (1.0f / 512.0f) + EPS); }
.LBB0_382:
	s_or_b64 exec, exec, s[16:17]
	s_waitcnt lgkmcnt(0)
	v_lshl_add_u64 v[6:7], s[4:5], 0, v[22:23]
	v_mad_u64_u32 v[52:53], s[16:17], v6, s45, v[44:45]
	v_mad_i32_i24 v53, v7, s45, v53
	v_mov_b32_e32 v52, v104
	v_mov_b32_e32 v53, v105
	v_mov_b32_e32 v54, v106
	v_mov_b32_e32 v55, v107
	v_and_b32_e32 v7, 0xffff0000, v52
	v_lshlrev_b32_e32 v6, 16, v52
	v_mul_f32_e32 v7, v7, v7
	v_lshlrev_b32_e32 v52, 16, v53
	v_fmac_f32_e32 v7, v6, v6
	v_and_b32_e32 v53, 0xffff0000, v53
	v_fmac_f32_e32 v7, v52, v52
	v_lshlrev_b32_e32 v56, 16, v54
	v_fmac_f32_e32 v7, v53, v53
	v_and_b32_e32 v54, 0xffff0000, v54
	v_fmac_f32_e32 v7, v56, v56
	v_lshlrev_b32_e32 v57, 16, v55
	v_fmac_f32_e32 v7, v54, v54
	v_and_b32_e32 v55, 0xffff0000, v55
	v_fmac_f32_e32 v7, v57, v57
	v_fmac_f32_e32 v7, v55, v55
	ds_bpermute_b32 v6, v0, v7
	s_waitcnt lgkmcnt(0)
	v_add_f32_e32 v6, v7, v6
	ds_bpermute_b32 v7, v1, v6
	s_waitcnt lgkmcnt(0)
	v_add_f32_e32 v6, v6, v7
	ds_bpermute_b32 v7, v2, v6
	s_waitcnt lgkmcnt(0)
	v_add_f32_e32 v6, v6, v7
	ds_bpermute_b32 v7, v3, v6
	s_waitcnt lgkmcnt(0)
	v_add_f32_e32 v6, v6, v7
	ds_bpermute_b32 v7, v4, v6
	s_waitcnt lgkmcnt(0)
	v_add_f32_e32 v6, v6, v7
	ds_bpermute_b32 v7, v5, v6
	s_and_saveexec_b64 s[16:17], s[14:15]
	s_cbranch_execz .LBB0_384
	s_waitcnt lgkmcnt(0)
	v_add_f32_e32 v6, v6, v7
	v_fmamk_f32 v6, v6, 0x3b000000, v208
	v_mul_f32_e32 v7, 0x4b800000, v6
	v_cmp_gt_f32_e32 vcc, s44, v6
	s_nop 1
	v_cndmask_b32_e32 v6, v6, v7, vcc
	v_rsq_f32_e32 v6, v6
	s_nop 0
	v_mul_f32_e32 v7, 0x45800000, v6
	v_cndmask_b32_e32 v6, v6, v7, vcc
	ds_write_b32 v69, v6 offset:20
.LBB0_384:
	s_or_b64 exec, exec, s[16:17]
	s_waitcnt lgkmcnt(0)
	v_lshl_add_u64 v[6:7], s[4:5], 0, v[24:25]
	v_mad_u64_u32 v[52:53], s[16:17], v6, s45, v[44:45]
	v_mad_i32_i24 v53, v7, s45, v53
	v_mov_b32_e32 v52, v108
	v_mov_b32_e32 v53, v109
	v_mov_b32_e32 v54, v110
	v_mov_b32_e32 v55, v111
	v_and_b32_e32 v7, 0xffff0000, v52
	v_lshlrev_b32_e32 v6, 16, v52
	v_mul_f32_e32 v7, v7, v7
	v_lshlrev_b32_e32 v52, 16, v53
	v_fmac_f32_e32 v7, v6, v6
	v_and_b32_e32 v53, 0xffff0000, v53
	v_fmac_f32_e32 v7, v52, v52
	v_lshlrev_b32_e32 v56, 16, v54
	v_fmac_f32_e32 v7, v53, v53
	v_and_b32_e32 v54, 0xffff0000, v54
	v_fmac_f32_e32 v7, v56, v56
	v_lshlrev_b32_e32 v57, 16, v55
	v_fmac_f32_e32 v7, v54, v54
	v_and_b32_e32 v55, 0xffff0000, v55
	v_fmac_f32_e32 v7, v57, v57
	v_fmac_f32_e32 v7, v55, v55
	ds_bpermute_b32 v6, v0, v7
	s_waitcnt lgkmcnt(0)
	v_add_f32_e32 v6, v7, v6
	ds_bpermute_b32 v7, v1, v6
	s_waitcnt lgkmcnt(0)
	v_add_f32_e32 v6, v6, v7
	ds_bpermute_b32 v7, v2, v6
	s_waitcnt lgkmcnt(0)
	v_add_f32_e32 v6, v6, v7
	ds_bpermute_b32 v7, v3, v6
	s_waitcnt lgkmcnt(0)
	v_add_f32_e32 v6, v6, v7
	ds_bpermute_b32 v7, v4, v6
	s_waitcnt lgkmcnt(0)
	v_add_f32_e32 v6, v6, v7
	ds_bpermute_b32 v7, v5, v6
	s_and_saveexec_b64 s[16:17], s[14:15]
	s_cbranch_execz .LBB0_386
	s_waitcnt lgkmcnt(0)
	v_add_f32_e32 v6, v6, v7
	v_fmamk_f32 v6, v6, 0x3b000000, v208
	v_mul_f32_e32 v7, 0x4b800000, v6
	v_cmp_gt_f32_e32 vcc, s44, v6
	s_nop 1
	v_cndmask_b32_e32 v6, v6, v7, vcc
	v_rsq_f32_e32 v6, v6
	s_nop 0
	v_mul_f32_e32 v7, 0x45800000, v6
	v_cndmask_b32_e32 v6, v6, v7, vcc
	ds_write_b32 v69, v6 offset:24
.LBB0_386:
	s_or_b64 exec, exec, s[16:17]
	s_waitcnt lgkmcnt(0)
	v_lshl_add_u64 v[6:7], s[4:5], 0, v[26:27]
	v_mad_u64_u32 v[52:53], s[16:17], v6, s45, v[44:45]
	v_mad_i32_i24 v53, v7, s45, v53
	v_mov_b32_e32 v52, v112
	v_mov_b32_e32 v53, v113
	v_mov_b32_e32 v54, v114
	v_mov_b32_e32 v55, v115
	v_and_b32_e32 v7, 0xffff0000, v52
	v_lshlrev_b32_e32 v6, 16, v52
	v_mul_f32_e32 v7, v7, v7
	v_lshlrev_b32_e32 v52, 16, v53
	v_fmac_f32_e32 v7, v6, v6
	v_and_b32_e32 v53, 0xffff0000, v53
	v_fmac_f32_e32 v7, v52, v52
	v_lshlrev_b32_e32 v56, 16, v54
	v_fmac_f32_e32 v7, v53, v53
	v_and_b32_e32 v54, 0xffff0000, v54
	v_fmac_f32_e32 v7, v56, v56
	v_lshlrev_b32_e32 v57, 16, v55
	v_fmac_f32_e32 v7, v54, v54
	v_and_b32_e32 v55, 0xffff0000, v55
	v_fmac_f32_e32 v7, v57, v57
	v_fmac_f32_e32 v7, v55, v55
	ds_bpermute_b32 v6, v0, v7
	s_waitcnt lgkmcnt(0)
	v_add_f32_e32 v6, v7, v6
	ds_bpermute_b32 v7, v1, v6
	s_waitcnt lgkmcnt(0)
	v_add_f32_e32 v6, v6, v7
	ds_bpermute_b32 v7, v2, v6
	s_waitcnt lgkmcnt(0)
	v_add_f32_e32 v6, v6, v7
	ds_bpermute_b32 v7, v3, v6
	s_waitcnt lgkmcnt(0)
	v_add_f32_e32 v6, v6, v7
	ds_bpermute_b32 v7, v4, v6
	s_waitcnt lgkmcnt(0)
	v_add_f32_e32 v6, v6, v7
	ds_bpermute_b32 v7, v5, v6
	s_and_saveexec_b64 s[16:17], s[14:15]
	s_cbranch_execz .LBB0_388
	s_waitcnt lgkmcnt(0)
	v_add_f32_e32 v6, v6, v7
	v_fmamk_f32 v6, v6, 0x3b000000, v208
	v_mul_f32_e32 v7, 0x4b800000, v6
	v_cmp_gt_f32_e32 vcc, s44, v6
	s_nop 1
	v_cndmask_b32_e32 v6, v6, v7, vcc
	v_rsq_f32_e32 v6, v6
	s_nop 0
	v_mul_f32_e32 v7, 0x45800000, v6
	v_cndmask_b32_e32 v6, v6, v7, vcc
	ds_write_b32 v69, v6 offset:28
.LBB0_388:
	s_or_b64 exec, exec, s[16:17]
	s_waitcnt lgkmcnt(0)
	v_lshl_add_u64 v[6:7], s[4:5], 0, v[28:29]
	v_mad_u64_u32 v[52:53], s[16:17], v6, s45, v[44:45]
	v_mad_i32_i24 v53, v7, s45, v53
	v_mov_b32_e32 v52, v116
	v_mov_b32_e32 v53, v117
	v_mov_b32_e32 v54, v118
	v_mov_b32_e32 v55, v119
	v_and_b32_e32 v7, 0xffff0000, v52
	v_lshlrev_b32_e32 v6, 16, v52
	v_mul_f32_e32 v7, v7, v7
	v_lshlrev_b32_e32 v52, 16, v53
	v_fmac_f32_e32 v7, v6, v6
	v_and_b32_e32 v53, 0xffff0000, v53
	v_fmac_f32_e32 v7, v52, v52
	v_lshlrev_b32_e32 v56, 16, v54
	v_fmac_f32_e32 v7, v53, v53
	v_and_b32_e32 v54, 0xffff0000, v54
	v_fmac_f32_e32 v7, v56, v56
	v_lshlrev_b32_e32 v57, 16, v55
	v_fmac_f32_e32 v7, v54, v54
	v_and_b32_e32 v55, 0xffff0000, v55
	v_fmac_f32_e32 v7, v57, v57
	v_fmac_f32_e32 v7, v55, v55
	ds_bpermute_b32 v6, v0, v7
	s_waitcnt lgkmcnt(0)
	v_add_f32_e32 v6, v7, v6
	ds_bpermute_b32 v7, v1, v6
	s_waitcnt lgkmcnt(0)
	v_add_f32_e32 v6, v6, v7
	ds_bpermute_b32 v7, v2, v6
	s_waitcnt lgkmcnt(0)
	v_add_f32_e32 v6, v6, v7
	ds_bpermute_b32 v7, v3, v6
	s_waitcnt lgkmcnt(0)
	v_add_f32_e32 v6, v6, v7
	ds_bpermute_b32 v7, v4, v6
	s_waitcnt lgkmcnt(0)
	v_add_f32_e32 v6, v6, v7
	ds_bpermute_b32 v7, v5, v6
	s_and_saveexec_b64 s[16:17], s[14:15]
	s_cbranch_execz .LBB0_390
	s_waitcnt lgkmcnt(0)
	v_add_f32_e32 v6, v6, v7
	v_fmamk_f32 v6, v6, 0x3b000000, v208
	v_mul_f32_e32 v7, 0x4b800000, v6
	v_cmp_gt_f32_e32 vcc, s44, v6
	s_nop 1
	v_cndmask_b32_e32 v6, v6, v7, vcc
	v_rsq_f32_e32 v6, v6
	s_nop 0
	v_mul_f32_e32 v7, 0x45800000, v6
	v_cndmask_b32_e32 v6, v6, v7, vcc
	ds_write_b32 v69, v6 offset:32
; __device__ __forceinline__ void UNPACK8(const u32x4 q, float (&f)[8]) { f[0] = bflo(q.x); f[1] = bfhi(q.x); f[2] = bflo(q.y); f[3] = bfhi(q.y); f[4] = bflo(q.z); f[5] = bfhi(q.z); f[6] = bflo(q.w); f[7] = bfhi(q.w); }
; __device__ __forceinline__ void sguprep_chunk(PCP p, int j, LAS unsigned char* lds, int it, int tid) {
;     ...
;         for (int s0 = 0; s0 < 16; ++s0) { const int s = wid * 16 + s0; const u32x4 vw = *(const u32x4*)(proj + (T0 + s) * 1536 + 1024 + lane * 8); float v[8]; UNPACK8(vw, v); float ss = 0.f;
; #pragma unroll
;             for (int e = 0; e < 8; ++e) ss += v[e] * v[e];
;             ss = wave_sum(ss); if (lane == 0) rstd[s] = rsqrtf(ss * (1.0f / 512.0f) + EPS); }
.LBB0_390:
	s_or_b64 exec, exec, s[16:17]
	s_waitcnt lgkmcnt(0)
	v_lshl_add_u64 v[6:7], s[4:5], 0, v[30:31]
	v_mad_u64_u32 v[52:53], s[16:17], v6, s45, v[44:45]
	v_mad_i32_i24 v53, v7, s45, v53
	v_mov_b32_e32 v52, v120
	v_mov_b32_e32 v53, v121
	v_mov_b32_e32 v54, v122
	v_mov_b32_e32 v55, v123
	v_and_b32_e32 v7, 0xffff0000, v52
	v_lshlrev_b32_e32 v6, 16, v52
	v_mul_f32_e32 v7, v7, v7
	v_lshlrev_b32_e32 v52, 16, v53
	v_fmac_f32_e32 v7, v6, v6
	v_and_b32_e32 v53, 0xffff0000, v53
	v_fmac_f32_e32 v7, v52, v52
	v_lshlrev_b32_e32 v56, 16, v54
	v_fmac_f32_e32 v7, v53, v53
	v_and_b32_e32 v54, 0xffff0000, v54
	v_fmac_f32_e32 v7, v56, v56
	v_lshlrev_b32_e32 v57, 16, v55
	v_fmac_f32_e32 v7, v54, v54
	v_and_b32_e32 v55, 0xffff0000, v55
	v_fmac_f32_e32 v7, v57, v57
	v_fmac_f32_e32 v7, v55, v55
	ds_bpermute_b32 v6, v0, v7
	s_waitcnt lgkmcnt(0)
	v_add_f32_e32 v6, v7, v6
	ds_bpermute_b32 v7, v1, v6
	s_waitcnt lgkmcnt(0)
	v_add_f32_e32 v6, v6, v7
	ds_bpermute_b32 v7, v2, v6
	s_waitcnt lgkmcnt(0)
	v_add_f32_e32 v6, v6, v7
	ds_bpermute_b32 v7, v3, v6
	s_waitcnt lgkmcnt(0)
	v_add_f32_e32 v6, v6, v7
	ds_bpermute_b32 v7, v4, v6
	s_waitcnt lgkmcnt(0)
	v_add_f32_e32 v6, v6, v7
	ds_bpermute_b32 v7, v5, v6
	s_and_saveexec_b64 s[16:17], s[14:15]
	s_cbranch_execz .LBB0_392
	s_waitcnt lgkmcnt(0)
	v_add_f32_e32 v6, v6, v7
	v_fmamk_f32 v6, v6, 0x3b000000, v208
	v_mul_f32_e32 v7, 0x4b800000, v6
	v_cmp_gt_f32_e32 vcc, s44, v6
	s_nop 1
	v_cndmask_b32_e32 v6, v6, v7, vcc
	v_rsq_f32_e32 v6, v6
	s_nop 0
	v_mul_f32_e32 v7, 0x45800000, v6
	v_cndmask_b32_e32 v6, v6, v7, vcc
	ds_write_b32 v69, v6 offset:36
.LBB0_392:
	s_or_b64 exec, exec, s[16:17]
	s_waitcnt lgkmcnt(0)
	v_lshl_add_u64 v[6:7], s[4:5], 0, v[32:33]
	v_mad_u64_u32 v[52:53], s[16:17], v6, s45, v[44:45]
	v_mad_i32_i24 v53, v7, s45, v53
	v_mov_b32_e32 v52, v124
	v_mov_b32_e32 v53, v125
	v_mov_b32_e32 v54, v126
	v_mov_b32_e32 v55, v127
	v_and_b32_e32 v7, 0xffff0000, v52
	v_lshlrev_b32_e32 v6, 16, v52
	v_mul_f32_e32 v7, v7, v7
	v_lshlrev_b32_e32 v52, 16, v53
	v_fmac_f32_e32 v7, v6, v6
	v_and_b32_e32 v53, 0xffff0000, v53
	v_fmac_f32_e32 v7, v52, v52
	v_lshlrev_b32_e32 v56, 16, v54
	v_fmac_f32_e32 v7, v53, v53
	v_and_b32_e32 v54, 0xffff0000, v54
	v_fmac_f32_e32 v7, v56, v56
	v_lshlrev_b32_e32 v57, 16, v55
	v_fmac_f32_e32 v7, v54, v54
	v_and_b32_e32 v55, 0xffff0000, v55
	v_fmac_f32_e32 v7, v57, v57
	v_fmac_f32_e32 v7, v55, v55
	ds_bpermute_b32 v6, v0, v7
	s_waitcnt lgkmcnt(0)
	v_add_f32_e32 v6, v7, v6
	ds_bpermute_b32 v7, v1, v6
	s_waitcnt lgkmcnt(0)
	v_add_f32_e32 v6, v6, v7
	ds_bpermute_b32 v7, v2, v6
	s_waitcnt lgkmcnt(0)
	v_add_f32_e32 v6, v6, v7
	ds_bpermute_b32 v7, v3, v6
	s_waitcnt lgkmcnt(0)
	v_add_f32_e32 v6, v6, v7
	ds_bpermute_b32 v7, v4, v6
	s_waitcnt lgkmcnt(0)
	v_add_f32_e32 v6, v6, v7
	ds_bpermute_b32 v7, v5, v6
	s_and_saveexec_b64 s[16:17], s[14:15]
	s_cbranch_execz .LBB0_394
	s_waitcnt lgkmcnt(0)
	v_add_f32_e32 v6, v6, v7
	v_fmamk_f32 v6, v6, 0x3b000000, v208
	v_mul_f32_e32 v7, 0x4b800000, v6
	v_cmp_gt_f32_e32 vcc, s44, v6
	s_nop 1
	v_cndmask_b32_e32 v6, v6, v7, vcc
	v_rsq_f32_e32 v6, v6
	s_nop 0
	v_mul_f32_e32 v7, 0x45800000, v6
	v_cndmask_b32_e32 v6, v6, v7, vcc
	ds_write_b32 v69, v6 offset:40
.LBB0_394:
	s_or_b64 exec, exec, s[16:17]
	s_waitcnt lgkmcnt(0)
	v_lshl_add_u64 v[6:7], s[4:5], 0, v[34:35]
	v_mad_u64_u32 v[52:53], s[16:17], v6, s45, v[44:45]
	v_mad_i32_i24 v53, v7, s45, v53
	v_mov_b32_e32 v52, v128
	v_mov_b32_e32 v53, v129
	v_mov_b32_e32 v54, v130
	v_mov_b32_e32 v55, v131
	v_and_b32_e32 v7, 0xffff0000, v52
	v_lshlrev_b32_e32 v6, 16, v52
	v_mul_f32_e32 v7, v7, v7
	v_lshlrev_b32_e32 v52, 16, v53
	v_fmac_f32_e32 v7, v6, v6
	v_and_b32_e32 v53, 0xffff0000, v53
	v_fmac_f32_e32 v7, v52, v52
	v_lshlrev_b32_e32 v56, 16, v54
	v_fmac_f32_e32 v7, v53, v53
	v_and_b32_e32 v54, 0xffff0000, v54
	v_fmac_f32_e32 v7, v56, v56
	v_lshlrev_b32_e32 v57, 16, v55
	v_fmac_f32_e32 v7, v54, v54
	v_and_b32_e32 v55, 0xffff0000, v55
	v_fmac_f32_e32 v7, v57, v57
	v_fmac_f32_e32 v7, v55, v55
	ds_bpermute_b32 v6, v0, v7
	s_waitcnt lgkmcnt(0)
	v_add_f32_e32 v6, v7, v6
	ds_bpermute_b32 v7, v1, v6
	s_waitcnt lgkmcnt(0)
	v_add_f32_e32 v6, v6, v7
	ds_bpermute_b32 v7, v2, v6
	s_waitcnt lgkmcnt(0)
	v_add_f32_e32 v6, v6, v7
	ds_bpermute_b32 v7, v3, v6
	s_waitcnt lgkmcnt(0)
	v_add_f32_e32 v6, v6, v7
	ds_bpermute_b32 v7, v4, v6
	s_waitcnt lgkmcnt(0)
	v_add_f32_e32 v6, v6, v7
	ds_bpermute_b32 v7, v5, v6
	s_and_saveexec_b64 s[16:17], s[14:15]
	s_cbranch_execz .LBB0_396
	s_waitcnt lgkmcnt(0)
	v_add_f32_e32 v6, v6, v7
	v_fmamk_f32 v6, v6, 0x3b000000, v208
	v_mul_f32_e32 v7, 0x4b800000, v6
	v_cmp_gt_f32_e32 vcc, s44, v6
	s_nop 1
	v_cndmask_b32_e32 v6, v6, v7, vcc
	v_rsq_f32_e32 v6, v6
	s_nop 0
	v_mul_f32_e32 v7, 0x45800000, v6
	v_cndmask_b32_e32 v6, v6, v7, vcc
	ds_write_b32 v69, v6 offset:44
; __device__ __forceinline__ void UNPACK8(const u32x4 q, float (&f)[8]) { f[0] = bflo(q.x); f[1] = bfhi(q.x); f[2] = bflo(q.y); f[3] = bfhi(q.y); f[4] = bflo(q.z); f[5] = bfhi(q.z); f[6] = bflo(q.w); f[7] = bfhi(q.w); }
; __device__ __forceinline__ void sguprep_chunk(PCP p, int j, LAS unsigned char* lds, int it, int tid) {
;     ...
;         for (int s0 = 0; s0 < 16; ++s0) { const int s = wid * 16 + s0; const u32x4 vw = *(const u32x4*)(proj + (T0 + s) * 1536 + 1024 + lane * 8); float v[8]; UNPACK8(vw, v); float ss = 0.f;
; #pragma unroll
;             for (int e = 0; e < 8; ++e) ss += v[e] * v[e];
;             ss = wave_sum(ss); if (lane == 0) rstd[s] = rsqrtf(ss * (1.0f / 512.0f) + EPS); }
.LBB0_396:
	s_or_b64 exec, exec, s[16:17]
	s_waitcnt lgkmcnt(0)
	v_lshl_add_u64 v[6:7], s[4:5], 0, v[36:37]
	v_mad_u64_u32 v[52:53], s[16:17], v6, s45, v[44:45]
	v_mad_i32_i24 v53, v7, s45, v53
	v_mov_b32_e32 v52, v132
	v_mov_b32_e32 v53, v133
	v_mov_b32_e32 v54, v134
	v_mov_b32_e32 v55, v135
	v_and_b32_e32 v7, 0xffff0000, v52
	v_lshlrev_b32_e32 v6, 16, v52
	v_mul_f32_e32 v7, v7, v7
	v_lshlrev_b32_e32 v52, 16, v53
	v_fmac_f32_e32 v7, v6, v6
	v_and_b32_e32 v53, 0xffff0000, v53
	v_fmac_f32_e32 v7, v52, v52
	v_lshlrev_b32_e32 v56, 16, v54
	v_fmac_f32_e32 v7, v53, v53
	v_and_b32_e32 v54, 0xffff0000, v54
	v_fmac_f32_e32 v7, v56, v56
	v_lshlrev_b32_e32 v57, 16, v55
	v_fmac_f32_e32 v7, v54, v54
	v_and_b32_e32 v55, 0xffff0000, v55
	v_fmac_f32_e32 v7, v57, v57
	v_fmac_f32_e32 v7, v55, v55
	ds_bpermute_b32 v6, v0, v7
	s_waitcnt lgkmcnt(0)
	v_add_f32_e32 v6, v7, v6
	ds_bpermute_b32 v7, v1, v6
	s_waitcnt lgkmcnt(0)
	v_add_f32_e32 v6, v6, v7
	ds_bpermute_b32 v7, v2, v6
	s_waitcnt lgkmcnt(0)
	v_add_f32_e32 v6, v6, v7
	ds_bpermute_b32 v7, v3, v6
	s_waitcnt lgkmcnt(0)
	v_add_f32_e32 v6, v6, v7
	ds_bpermute_b32 v7, v4, v6
	s_waitcnt lgkmcnt(0)
	v_add_f32_e32 v6, v6, v7
	ds_bpermute_b32 v7, v5, v6
	s_and_saveexec_b64 s[16:17], s[14:15]
	s_cbranch_execz .LBB0_398
	s_waitcnt lgkmcnt(0)
	v_add_f32_e32 v6, v6, v7
	v_fmamk_f32 v6, v6, 0x3b000000, v208
	v_mul_f32_e32 v7, 0x4b800000, v6
	v_cmp_gt_f32_e32 vcc, s44, v6
	s_nop 1
	v_cndmask_b32_e32 v6, v6, v7, vcc
	v_rsq_f32_e32 v6, v6
	s_nop 0
	v_mul_f32_e32 v7, 0x45800000, v6
	v_cndmask_b32_e32 v6, v6, v7, vcc
	ds_write_b32 v69, v6 offset:48
.LBB0_398:
	s_or_b64 exec, exec, s[16:17]
	s_waitcnt lgkmcnt(0)
	v_lshl_add_u64 v[6:7], s[4:5], 0, v[38:39]
	v_mad_u64_u32 v[52:53], s[16:17], v6, s45, v[44:45]
	v_mad_i32_i24 v53, v7, s45, v53
	v_mov_b32_e32 v52, v136
	v_mov_b32_e32 v53, v137
	v_mov_b32_e32 v54, v138
	v_mov_b32_e32 v55, v139
	v_and_b32_e32 v7, 0xffff0000, v52
	v_lshlrev_b32_e32 v6, 16, v52
	v_mul_f32_e32 v7, v7, v7
	v_lshlrev_b32_e32 v52, 16, v53
	v_fmac_f32_e32 v7, v6, v6
	v_and_b32_e32 v53, 0xffff0000, v53
	v_fmac_f32_e32 v7, v52, v52
	v_lshlrev_b32_e32 v56, 16, v54
	v_fmac_f32_e32 v7, v53, v53
	v_and_b32_e32 v54, 0xffff0000, v54
	v_fmac_f32_e32 v7, v56, v56
	v_lshlrev_b32_e32 v57, 16, v55
	v_fmac_f32_e32 v7, v54, v54
	v_and_b32_e32 v55, 0xffff0000, v55
	v_fmac_f32_e32 v7, v57, v57
	v_fmac_f32_e32 v7, v55, v55
	ds_bpermute_b32 v6, v0, v7
	s_waitcnt lgkmcnt(0)
	v_add_f32_e32 v6, v7, v6
	ds_bpermute_b32 v7, v1, v6
	s_waitcnt lgkmcnt(0)
	v_add_f32_e32 v6, v6, v7
	ds_bpermute_b32 v7, v2, v6
	s_waitcnt lgkmcnt(0)
	v_add_f32_e32 v6, v6, v7
	ds_bpermute_b32 v7, v3, v6
	s_waitcnt lgkmcnt(0)
	v_add_f32_e32 v6, v6, v7
	ds_bpermute_b32 v7, v4, v6
	s_waitcnt lgkmcnt(0)
	v_add_f32_e32 v6, v6, v7
	ds_bpermute_b32 v7, v5, v6
	s_and_saveexec_b64 s[16:17], s[14:15]
	s_cbranch_execz .LBB0_400
	s_waitcnt lgkmcnt(0)
	v_add_f32_e32 v6, v6, v7
	v_fmamk_f32 v6, v6, 0x3b000000, v208
	v_mul_f32_e32 v7, 0x4b800000, v6
	v_cmp_gt_f32_e32 vcc, s44, v6
	s_nop 1
	v_cndmask_b32_e32 v6, v6, v7, vcc
	v_rsq_f32_e32 v6, v6
	s_nop 0
	v_mul_f32_e32 v7, 0x45800000, v6
	v_cndmask_b32_e32 v6, v6, v7, vcc
	ds_write_b32 v69, v6 offset:52
.LBB0_400:
	s_or_b64 exec, exec, s[16:17]
	s_waitcnt lgkmcnt(0)
	v_lshl_add_u64 v[6:7], s[4:5], 0, v[40:41]
	v_mad_u64_u32 v[52:53], s[16:17], v6, s45, v[44:45]
	v_mad_i32_i24 v53, v7, s45, v53
	v_mov_b32_e32 v52, v140
	v_mov_b32_e32 v53, v141
	v_mov_b32_e32 v54, v142
	v_mov_b32_e32 v55, v143
	v_and_b32_e32 v7, 0xffff0000, v52
	v_lshlrev_b32_e32 v6, 16, v52
	v_mul_f32_e32 v7, v7, v7
	v_lshlrev_b32_e32 v52, 16, v53
	v_fmac_f32_e32 v7, v6, v6
	v_and_b32_e32 v53, 0xffff0000, v53
	v_fmac_f32_e32 v7, v52, v52
	v_lshlrev_b32_e32 v56, 16, v54
	v_fmac_f32_e32 v7, v53, v53
	v_and_b32_e32 v54, 0xffff0000, v54
	v_fmac_f32_e32 v7, v56, v56
	v_lshlrev_b32_e32 v57, 16, v55
	v_fmac_f32_e32 v7, v54, v54
	v_and_b32_e32 v55, 0xffff0000, v55
	v_fmac_f32_e32 v7, v57, v57
	v_fmac_f32_e32 v7, v55, v55
	ds_bpermute_b32 v6, v0, v7
	s_waitcnt lgkmcnt(0)
	v_add_f32_e32 v6, v7, v6
	ds_bpermute_b32 v7, v1, v6
	s_waitcnt lgkmcnt(0)
	v_add_f32_e32 v6, v6, v7
	ds_bpermute_b32 v7, v2, v6
	s_waitcnt lgkmcnt(0)
	v_add_f32_e32 v6, v6, v7
	ds_bpermute_b32 v7, v3, v6
	s_waitcnt lgkmcnt(0)
	v_add_f32_e32 v6, v6, v7
	ds_bpermute_b32 v7, v4, v6
	s_waitcnt lgkmcnt(0)
	v_add_f32_e32 v6, v6, v7
	ds_bpermute_b32 v7, v5, v6
	s_and_saveexec_b64 s[16:17], s[14:15]
	s_cbranch_execz .LBB0_402
	s_waitcnt lgkmcnt(0)
	v_add_f32_e32 v6, v6, v7
	v_fmamk_f32 v6, v6, 0x3b000000, v208
	v_mul_f32_e32 v7, 0x4b800000, v6
	v_cmp_gt_f32_e32 vcc, s44, v6
	s_nop 1
	v_cndmask_b32_e32 v6, v6, v7, vcc
	v_rsq_f32_e32 v6, v6
	s_nop 0
	v_mul_f32_e32 v7, 0x45800000, v6
	v_cndmask_b32_e32 v6, v6, v7, vcc
	ds_write_b32 v69, v6 offset:56
.LBB0_402:
	s_or_b64 exec, exec, s[16:17]
	s_waitcnt lgkmcnt(0)
	v_lshl_add_u64 v[6:7], s[4:5], 0, v[42:43]
	v_mad_u64_u32 v[52:53], s[4:5], v6, s45, v[44:45]
	v_mad_i32_i24 v53, v7, s45, v53
	v_mov_b32_e32 v52, v144
	v_mov_b32_e32 v53, v145
	v_mov_b32_e32 v54, v146
	v_mov_b32_e32 v55, v147
	v_and_b32_e32 v7, 0xffff0000, v52
	v_lshlrev_b32_e32 v6, 16, v52
	v_mul_f32_e32 v7, v7, v7
	v_lshlrev_b32_e32 v52, 16, v53
	v_fmac_f32_e32 v7, v6, v6
	v_and_b32_e32 v53, 0xffff0000, v53
	v_fmac_f32_e32 v7, v52, v52
	v_lshlrev_b32_e32 v56, 16, v54
	v_fmac_f32_e32 v7, v53, v53
	v_and_b32_e32 v54, 0xffff0000, v54
	v_fmac_f32_e32 v7, v56, v56
	v_lshlrev_b32_e32 v57, 16, v55
	v_fmac_f32_e32 v7, v54, v54
	v_and_b32_e32 v55, 0xffff0000, v55
	v_fmac_f32_e32 v7, v57, v57
	v_fmac_f32_e32 v7, v55, v55
	ds_bpermute_b32 v0, v0, v7
	s_waitcnt lgkmcnt(0)
	v_add_f32_e32 v0, v7, v0
	ds_bpermute_b32 v1, v1, v0
	s_waitcnt lgkmcnt(0)
	v_add_f32_e32 v0, v0, v1
	ds_bpermute_b32 v1, v2, v0
	s_waitcnt lgkmcnt(0)
	v_add_f32_e32 v0, v0, v1
	ds_bpermute_b32 v1, v3, v0
	s_waitcnt lgkmcnt(0)
	v_add_f32_e32 v0, v0, v1
	ds_bpermute_b32 v1, v4, v0
	s_waitcnt lgkmcnt(0)
	v_add_f32_e32 v0, v0, v1
	ds_bpermute_b32 v1, v5, v0
	s_and_saveexec_b64 s[4:5], s[14:15]
	s_cbranch_execz .LBB0_404
	s_waitcnt lgkmcnt(0)
	v_add_f32_e32 v0, v0, v1
	v_fmamk_f32 v0, v0, 0x3b000000, v208
	v_mul_f32_e32 v1, 0x4b800000, v0
	v_cmp_gt_f32_e32 vcc, s44, v0
	s_nop 1
	v_cndmask_b32_e32 v0, v0, v1, vcc
	v_rsq_f32_e32 v0, v0
	s_nop 0
	v_mul_f32_e32 v1, 0x45800000, v0
	v_cndmask_b32_e32 v0, v0, v1, vcc
	ds_write_b32 v70, v0

; __device__ __forceinline__ void UNPACK8(const u32x4 q, float (&f)[8]) { f[0] = bflo(q.x); f[1] = bfhi(q.x); f[2] = bflo(q.y); f[3] = bfhi(q.y); f[4] = bflo(q.z); f[5] = bfhi(q.z); f[6] = bflo(q.w); f[7] = bfhi(q.w); }
; __device__ __forceinline__ void pool_chunk(PCP p, int chunk, int tid) {
;     ...
;         for (int k = 1; k < 16; ++k) { if (k < w && k <= pos0) { const u32x4 zw = *(const u32x4*)(proj + (size_t)(t0 - k) * 1536 + c); float q[8]; UNPACK8(zw, q);
; #pragma unroll
;             for (int e = 0; e < 8; ++e) s[e] += q[e]; } }
.LBB0_408:
	v_add_u32_e32 v5, -2, v4
	v_mad_i64_i32 v[52:53], s[28:29], v5, s45, v[8:9]
	v_mov_b32_e32 v56, v88
	v_mov_b32_e32 v57, v89
	v_mov_b32_e32 v58, v90
	v_mov_b32_e32 v59, v91
	v_lshlrev_b32_e32 v52, 16, v56
	v_and_b32_e32 v53, 0xffff0000, v56
	v_pk_add_f32 v[0:1], v[0:1], v[52:53]
	v_lshlrev_b32_e32 v52, 16, v57
	v_and_b32_e32 v53, 0xffff0000, v57
	v_pk_add_f32 v[2:3], v[2:3], v[52:53]
	v_lshlrev_b32_e32 v52, 16, v58
	v_and_b32_e32 v53, 0xffff0000, v58
	v_pk_add_f32 v[6:7], v[6:7], v[52:53]
	v_lshlrev_b32_e32 v52, 16, v59
	v_and_b32_e32 v53, 0xffff0000, v59
	v_pk_add_f32 v[52:53], v[54:55], v[52:53]
	s_or_b64 exec, exec, s[16:17]
	s_and_saveexec_b64 s[16:17], s[4:5]
	s_cbranch_execnz .LBB0_329

; __device__ __forceinline__ void UNPACK8(const u32x4 q, float (&f)[8]) { f[0] = bflo(q.x); f[1] = bfhi(q.x); f[2] = bflo(q.y); f[3] = bfhi(q.y); f[4] = bflo(q.z); f[5] = bfhi(q.z); f[6] = bflo(q.w); f[7] = bfhi(q.w); }
; __device__ __forceinline__ void pool_chunk(PCP p, int chunk, int tid) {
;     ...
;         for (int k = 1; k < 16; ++k) { if (k < w && k <= pos0) { const u32x4 zw = *(const u32x4*)(proj + (size_t)(t0 - k) * 1536 + c); float q[8]; UNPACK8(zw, q);
; #pragma unroll
;             for (int e = 0; e < 8; ++e) s[e] += q[e]; } }
.LBB0_410:
	v_add_u32_e32 v5, -4, v4
	v_mad_i64_i32 v[54:55], s[28:29], v5, s45, v[8:9]
	v_mov_b32_e32 v54, v96
	v_mov_b32_e32 v55, v97
	v_mov_b32_e32 v56, v98
	v_mov_b32_e32 v57, v99
	v_lshlrev_b32_e32 v58, 16, v54
	v_and_b32_e32 v59, 0xffff0000, v54
	v_lshlrev_b32_e32 v54, 16, v55
	v_and_b32_e32 v55, 0xffff0000, v55
	v_pk_add_f32 v[2:3], v[2:3], v[54:55]
	v_lshlrev_b32_e32 v54, 16, v56
	v_and_b32_e32 v55, 0xffff0000, v56
	v_pk_add_f32 v[6:7], v[6:7], v[54:55]
	v_lshlrev_b32_e32 v54, 16, v57
	v_and_b32_e32 v55, 0xffff0000, v57
	v_pk_add_f32 v[0:1], v[0:1], v[58:59]
	v_pk_add_f32 v[52:53], v[52:53], v[54:55]
	s_or_b64 exec, exec, s[16:17]
	s_and_saveexec_b64 s[16:17], s[4:5]
	s_cbranch_execnz .LBB0_331

; __device__ __forceinline__ void UNPACK8(const u32x4 q, float (&f)[8]) { f[0] = bflo(q.x); f[1] = bfhi(q.x); f[2] = bflo(q.y); f[3] = bfhi(q.y); f[4] = bflo(q.z); f[5] = bfhi(q.z); f[6] = bflo(q.w); f[7] = bfhi(q.w); }
; __device__ __forceinline__ void pool_chunk(PCP p, int chunk, int tid) {
;     ...
;         for (int k = 1; k < 16; ++k) { if (k < w && k <= pos0) { const u32x4 zw = *(const u32x4*)(proj + (size_t)(t0 - k) * 1536 + c); float q[8]; UNPACK8(zw, q);
; #pragma unroll
;             for (int e = 0; e < 8; ++e) s[e] += q[e]; } }
.LBB0_412:
	v_add_u32_e32 v5, -6, v4
	v_mad_i64_i32 v[54:55], s[28:29], v5, s45, v[8:9]
	v_mov_b32_e32 v54, v104
	v_mov_b32_e32 v55, v105
	v_mov_b32_e32 v56, v106
	v_mov_b32_e32 v57, v107
	v_lshlrev_b32_e32 v58, 16, v54
	v_and_b32_e32 v59, 0xffff0000, v54
	v_lshlrev_b32_e32 v54, 16, v55
	v_and_b32_e32 v55, 0xffff0000, v55
	v_pk_add_f32 v[2:3], v[2:3], v[54:55]
	v_lshlrev_b32_e32 v54, 16, v56
	v_and_b32_e32 v55, 0xffff0000, v56
	v_pk_add_f32 v[6:7], v[6:7], v[54:55]
	v_lshlrev_b32_e32 v54, 16, v57
	v_and_b32_e32 v55, 0xffff0000, v57
	v_pk_add_f32 v[0:1], v[0:1], v[58:59]
	v_pk_add_f32 v[52:53], v[52:53], v[54:55]
	s_or_b64 exec, exec, s[16:17]
	s_and_saveexec_b64 s[16:17], s[4:5]
	s_cbranch_execnz .LBB0_333

; __device__ __forceinline__ void UNPACK8(const u32x4 q, float (&f)[8]) { f[0] = bflo(q.x); f[1] = bfhi(q.x); f[2] = bflo(q.y); f[3] = bfhi(q.y); f[4] = bflo(q.z); f[5] = bfhi(q.z); f[6] = bflo(q.w); f[7] = bfhi(q.w); }
; __device__ __forceinline__ void pool_chunk(PCP p, int chunk, int tid) {
;     ...
;         for (int k = 1; k < 16; ++k) { if (k < w && k <= pos0) { const u32x4 zw = *(const u32x4*)(proj + (size_t)(t0 - k) * 1536 + c); float q[8]; UNPACK8(zw, q);
; #pragma unroll
;             for (int e = 0; e < 8; ++e) s[e] += q[e]; } }
.LBB0_414:
	v_add_u32_e32 v5, -8, v4
	v_mad_i64_i32 v[54:55], s[28:29], v5, s45, v[8:9]
	v_mov_b32_e32 v54, v112
	v_mov_b32_e32 v55, v113
	v_mov_b32_e32 v56, v114
	v_mov_b32_e32 v57, v115
	v_lshlrev_b32_e32 v58, 16, v54
	v_and_b32_e32 v59, 0xffff0000, v54
	v_lshlrev_b32_e32 v54, 16, v55
	v_and_b32_e32 v55, 0xffff0000, v55
	v_pk_add_f32 v[2:3], v[2:3], v[54:55]
	v_lshlrev_b32_e32 v54, 16, v56
	v_and_b32_e32 v55, 0xffff0000, v56
	v_pk_add_f32 v[6:7], v[6:7], v[54:55]
	v_lshlrev_b32_e32 v54, 16, v57
	v_and_b32_e32 v55, 0xffff0000, v57
	v_pk_add_f32 v[0:1], v[0:1], v[58:59]
	v_pk_add_f32 v[52:53], v[52:53], v[54:55]
	s_or_b64 exec, exec, s[16:17]
	s_and_saveexec_b64 s[16:17], s[4:5]
	s_cbranch_execnz .LBB0_335

; __device__ __forceinline__ void UNPACK8(const u32x4 q, float (&f)[8]) { f[0] = bflo(q.x); f[1] = bfhi(q.x); f[2] = bflo(q.y); f[3] = bfhi(q.y); f[4] = bflo(q.z); f[5] = bfhi(q.z); f[6] = bflo(q.w); f[7] = bfhi(q.w); }
; __device__ __forceinline__ void pool_chunk(PCP p, int chunk, int tid) {
;     ...
;         for (int k = 1; k < 16; ++k) { if (k < w && k <= pos0) { const u32x4 zw = *(const u32x4*)(proj + (size_t)(t0 - k) * 1536 + c); float q[8]; UNPACK8(zw, q);
; #pragma unroll
;             for (int e = 0; e < 8; ++e) s[e] += q[e]; } }
.LBB0_416:
	v_add_u32_e32 v5, -10, v4
	v_mad_i64_i32 v[54:55], s[28:29], v5, s45, v[8:9]
	v_mov_b32_e32 v54, v120
	v_mov_b32_e32 v55, v121
	v_mov_b32_e32 v56, v122
	v_mov_b32_e32 v57, v123
	v_lshlrev_b32_e32 v58, 16, v54
	v_and_b32_e32 v59, 0xffff0000, v54
	v_lshlrev_b32_e32 v54, 16, v55
	v_and_b32_e32 v55, 0xffff0000, v55
	v_pk_add_f32 v[2:3], v[2:3], v[54:55]
	v_lshlrev_b32_e32 v54, 16, v56
	v_and_b32_e32 v55, 0xffff0000, v56
	v_pk_add_f32 v[6:7], v[6:7], v[54:55]
	v_lshlrev_b32_e32 v54, 16, v57
	v_and_b32_e32 v55, 0xffff0000, v57
	v_pk_add_f32 v[0:1], v[0:1], v[58:59]
	v_pk_add_f32 v[52:53], v[52:53], v[54:55]
	s_or_b64 exec, exec, s[16:17]
	s_and_saveexec_b64 s[16:17], s[4:5]
	s_cbranch_execnz .LBB0_337

; __device__ __forceinline__ void UNPACK8(const u32x4 q, float (&f)[8]) { f[0] = bflo(q.x); f[1] = bfhi(q.x); f[2] = bflo(q.y); f[3] = bfhi(q.y); f[4] = bflo(q.z); f[5] = bfhi(q.z); f[6] = bflo(q.w); f[7] = bfhi(q.w); }
; __device__ __forceinline__ void pool_chunk(PCP p, int chunk, int tid) {
;     ...
;         for (int k = 1; k < 16; ++k) { if (k < w && k <= pos0) { const u32x4 zw = *(const u32x4*)(proj + (size_t)(t0 - k) * 1536 + c); float q[8]; UNPACK8(zw, q);
; #pragma unroll
;             for (int e = 0; e < 8; ++e) s[e] += q[e]; } }
.LBB0_418:
	v_add_u32_e32 v5, -12, v4
	v_mad_i64_i32 v[54:55], s[28:29], v5, s45, v[8:9]
	v_mov_b32_e32 v54, v128
	v_mov_b32_e32 v55, v129
	v_mov_b32_e32 v56, v130
	v_mov_b32_e32 v57, v131
	v_lshlrev_b32_e32 v58, 16, v54
	v_and_b32_e32 v59, 0xffff0000, v54
	v_lshlrev_b32_e32 v54, 16, v55
	v_and_b32_e32 v55, 0xffff0000, v55
	v_pk_add_f32 v[2:3], v[2:3], v[54:55]
	v_lshlrev_b32_e32 v54, 16, v56
	v_and_b32_e32 v55, 0xffff0000, v56
	v_pk_add_f32 v[6:7], v[6:7], v[54:55]
	v_lshlrev_b32_e32 v54, 16, v57
	v_and_b32_e32 v55, 0xffff0000, v57
	v_pk_add_f32 v[0:1], v[0:1], v[58:59]
	v_pk_add_f32 v[52:53], v[52:53], v[54:55]
	s_or_b64 exec, exec, s[16:17]
	s_and_saveexec_b64 s[16:17], s[4:5]
	s_cbranch_execnz .LBB0_339

; __device__ __forceinline__ void UNPACK8(const u32x4 q, float (&f)[8]) { f[0] = bflo(q.x); f[1] = bfhi(q.x); f[2] = bflo(q.y); f[3] = bfhi(q.y); f[4] = bflo(q.z); f[5] = bfhi(q.z); f[6] = bflo(q.w); f[7] = bfhi(q.w); }
; __device__ __forceinline__ void pool_chunk(PCP p, int chunk, int tid) {
;     ...
;         for (int k = 1; k < 16; ++k) { if (k < w && k <= pos0) { const u32x4 zw = *(const u32x4*)(proj + (size_t)(t0 - k) * 1536 + c); float q[8]; UNPACK8(zw, q);
; #pragma unroll
;             for (int e = 0; e < 8; ++e) s[e] += q[e]; } }
.LBB0_420:
	v_add_u32_e32 v5, -14, v4
	v_mad_i64_i32 v[54:55], s[28:29], v5, s45, v[8:9]
	v_mov_b32_e32 v54, v136
	v_mov_b32_e32 v55, v137
	v_mov_b32_e32 v56, v138
	v_mov_b32_e32 v57, v139
	v_lshlrev_b32_e32 v58, 16, v54
	v_and_b32_e32 v59, 0xffff0000, v54
	v_lshlrev_b32_e32 v54, 16, v55
	v_and_b32_e32 v55, 0xffff0000, v55
	v_pk_add_f32 v[2:3], v[2:3], v[54:55]
	v_lshlrev_b32_e32 v54, 16, v56
	v_and_b32_e32 v55, 0xffff0000, v56
	v_pk_add_f32 v[6:7], v[6:7], v[54:55]
	v_lshlrev_b32_e32 v54, 16, v57
	v_and_b32_e32 v55, 0xffff0000, v57
	v_pk_add_f32 v[0:1], v[0:1], v[58:59]
	v_pk_add_f32 v[52:53], v[52:53], v[54:55]
	s_or_b64 exec, exec, s[16:17]
	s_and_saveexec_b64 s[16:17], s[4:5]
	s_cbranch_execnz .LBB0_341
	s_branch .LBB0_342
